# scan loops: 48 dead scalar instructions removed (row-1/row-3 base computations left by the paired finish stores, flag inits overwritten before any read)
# baseline (speedup 1.0000x reference)
; __device__ __forceinline__ float row16_sum(float v) { v += dppf<0xB1>(v); v += dppf<0x4E>(v); v += dppf<0x141>(v); v += dppf<0x140>(v); return v; }
; __device__ __forceinline__ float frsq(float x) { return __builtin_amdgcn_rsqf(x); }
; __device__ __forceinline__ v2u pack4(const f32x4 v) { v2u r; r.x = pk2(v[0], v[1]); r.y = pk2(v[2], v[3]); return r; }
; __device__ __forceinline__ f32x4 unpack4(const v2u w) { f32x4 r; r[0] = bflo(w.x); r[1] = bfhi(w.x); r[2] = bflo(w.y); r[3] = bfhi(w.y); return r; }
; __device__ __forceinline__ const char* upin(const char* p) { asm volatile("" : "+s"(p)); return p; }
; __device__ __forceinline__ char* upin(char* p) { asm volatile("" : "+s"(p)); return p; }
; template <bool GDN> __device__ __forceinline__ void scan_finish(const Frame& F, int b, int h, int dir, const ScanLane& L, int s, float* PEND, const f32x4 (&Oin)[4], const ScanFin& f) {
;     ...
;         f32x4 O[4]; float ss[4] = {0.f, 0.f, 0.f, 0.f};
; #pragma unroll
;         for (int t = 0; t < 4; ++t)
;             { const f32x4 pv = unpack4(f.pend[t]);
; #pragma unroll
;             for (int i = 0; i < 4; ++i) { O[t][i] = Oin[t][i] + pv[i]; ss[i] += O[t][i] * O[t][i]; } }
; #pragma unroll
;         for (int i = 0; i < 4; ++i) ss[i] = frsq(row16_sum(ss[i]) * (1.f / 64.f) + EPS);
;         char* mp = (char*)F.MIX + ((size_t)row0 * 1024 + (GDN ? 0 : 768) + h * 64) * 2;
; #pragma unroll
;         for (int i = 0; i < 4; ++i) { const f32x4 g = unpack4(f.gz[i]); f32x4 ov;
; #pragma unroll
;             for (int t = 0; t < 4; ++t) ov[t] = O[t][i] * ss[i] * g[t];
;             stu<v2u>(upin(mp + i * 2048), L.mix, pack4(ov)); }
;     ...
;     __syncthreads();
;     if (s > 0) {
;         const int sp = s - 1;
;         if (sp == 20 || sp == 2) { asm volatile("s_waitcnt vmcnt(0)" ::: "memory"); scan_fin_load<GDN>(F, b, h, dir, L, sp, PEND, fin); }
;         if (!nofin) scan_finish<GDN>(F, b, h, dir, L, sp, PEND, Oprev, fin);
.LBB0_352:
	s_add_i32 s0, s25, -1
	s_cmp_eq_u32 s25, 0
	s_cselect_b64 s[10:11], -1, 0
	s_and_b64 vcc, exec, s[10:11]
	s_waitcnt lgkmcnt(0)
	s_barrier
	s_cbranch_vccnz .LBB0_357
	s_add_i32 s1, s24, 43
	s_and_b64 s[4:5], s[90:91], exec
	s_cselect_b32 s1, s0, s1
	s_cmp_lt_u32 s25, 5
	s_cselect_b32 s3, 2, 20
	s_cmp_lt_u32 s0, s3
	s_mov_b64 s[12:13], -1
	s_cbranch_scc1 .LBB0_355
	s_lshl_b32 s3, s1, 6
	s_cmp_lt_i32 s1, 4
	s_cselect_b32 s4, s63, s33
	s_add_i32 s4, s4, s3
	s_ashr_i32 s5, s4, 31
	s_lshl_b64 s[4:5], s[4:5], 11
	s_add_u32 s3, s26, s4
	s_addc_u32 s4, s27, s5
	s_add_u32 s6, s3, 0x600
	s_addc_u32 s7, s4, 0
	v_lshlrev_b32_e32 v208, 16, v12
	v_and_b32_e32 v209, 0xffff0000, v12
	v_lshlrev_b32_e32 v210, 16, v13
	v_and_b32_e32 v211, 0xffff0000, v13
	v_pk_add_f32 v[212:213], v[104:105], v[208:209]
	v_pk_add_f32 v[214:215], v[106:107], v[210:211]
	v_pk_mul_f32 v[204:205], v[212:213], v[212:213]
	v_pk_mul_f32 v[206:207], v[214:215], v[214:215]
	v_lshlrev_b32_e32 v208, 16, v14
	v_and_b32_e32 v209, 0xffff0000, v14
	v_lshlrev_b32_e32 v210, 16, v15
	v_and_b32_e32 v211, 0xffff0000, v15
	v_pk_add_f32 v[216:217], v[108:109], v[208:209]
	v_pk_add_f32 v[218:219], v[110:111], v[210:211]
	v_pk_fma_f32 v[204:205], v[216:217], v[216:217], v[204:205]
	v_pk_fma_f32 v[206:207], v[218:219], v[218:219], v[206:207]
	v_lshlrev_b32_e32 v208, 16, v16
	v_and_b32_e32 v209, 0xffff0000, v16
	v_lshlrev_b32_e32 v210, 16, v17
	v_and_b32_e32 v211, 0xffff0000, v17
	v_pk_add_f32 v[224:225], v[112:113], v[208:209]
	v_pk_add_f32 v[226:227], v[114:115], v[210:211]
	v_pk_fma_f32 v[204:205], v[224:225], v[224:225], v[204:205]
	v_pk_fma_f32 v[206:207], v[226:227], v[226:227], v[206:207]
	v_lshlrev_b32_e32 v208, 16, v18
	v_and_b32_e32 v209, 0xffff0000, v18
	v_lshlrev_b32_e32 v210, 16, v19
	v_and_b32_e32 v211, 0xffff0000, v19
	v_pk_add_f32 v[242:243], v[116:117], v[208:209]
	v_pk_add_f32 v[244:245], v[118:119], v[210:211]
	v_pk_fma_f32 v[204:205], v[242:243], v[242:243], v[204:205]
	v_pk_fma_f32 v[206:207], v[244:245], v[244:245], v[206:207]
	s_nop 1
	v_add_f32_dpp v204, v204, v204 quad_perm:[1,0,3,2] row_mask:0xf bank_mask:0xf bound_ctrl:1
	v_add_f32_dpp v205, v205, v205 quad_perm:[1,0,3,2] row_mask:0xf bank_mask:0xf bound_ctrl:1
	v_add_f32_dpp v206, v206, v206 quad_perm:[1,0,3,2] row_mask:0xf bank_mask:0xf bound_ctrl:1
	v_add_f32_dpp v207, v207, v207 quad_perm:[1,0,3,2] row_mask:0xf bank_mask:0xf bound_ctrl:1
	v_add_f32_dpp v204, v204, v204 quad_perm:[2,3,0,1] row_mask:0xf bank_mask:0xf bound_ctrl:1
	v_add_f32_dpp v205, v205, v205 quad_perm:[2,3,0,1] row_mask:0xf bank_mask:0xf bound_ctrl:1
	v_add_f32_dpp v206, v206, v206 quad_perm:[2,3,0,1] row_mask:0xf bank_mask:0xf bound_ctrl:1
	v_add_f32_dpp v207, v207, v207 quad_perm:[2,3,0,1] row_mask:0xf bank_mask:0xf bound_ctrl:1
	v_add_f32_dpp v204, v204, v204 row_half_mirror row_mask:0xf bank_mask:0xf bound_ctrl:1
	v_add_f32_dpp v205, v205, v205 row_half_mirror row_mask:0xf bank_mask:0xf bound_ctrl:1
	v_add_f32_dpp v206, v206, v206 row_half_mirror row_mask:0xf bank_mask:0xf bound_ctrl:1
	v_add_f32_dpp v207, v207, v207 row_half_mirror row_mask:0xf bank_mask:0xf bound_ctrl:1
	v_add_f32_dpp v204, v204, v204 row_mirror row_mask:0xf bank_mask:0xf bound_ctrl:1
	v_add_f32_dpp v205, v205, v205 row_mirror row_mask:0xf bank_mask:0xf bound_ctrl:1
	v_add_f32_dpp v206, v206, v206 row_mirror row_mask:0xf bank_mask:0xf bound_ctrl:1
	v_add_f32_dpp v207, v207, v207 row_mirror row_mask:0xf bank_mask:0xf bound_ctrl:1
	v_fmamk_f32 v204, v204, 0x3c800000, v231
	v_fmamk_f32 v205, v205, 0x3c800000, v231
	v_fmamk_f32 v206, v206, 0x3c800000, v231
	v_fmamk_f32 v207, v207, 0x3c800000, v231
	v_rsq_f32_e32 v204, v204
	v_rsq_f32_e32 v205, v205
	v_rsq_f32_e32 v206, v206
	v_rsq_f32_e32 v207, v207
	v_lshlrev_b32_e32 v208, 16, v130
	v_lshlrev_b32_e32 v209, 16, v132
	v_lshlrev_b32_e32 v210, 16, v134
	v_lshlrev_b32_e32 v211, 16, v136
	v_pk_mul_f32 v[212:213], v[212:213], v[204:205]
	v_pk_mul_f32 v[214:215], v[214:215], v[206:207]
	v_pk_mul_f32 v[212:213], v[212:213], v[208:209]
	v_pk_mul_f32 v[214:215], v[214:215], v[210:211]
	v_and_b32_e32 v208, 0xffff0000, v130
	v_and_b32_e32 v209, 0xffff0000, v132
	v_and_b32_e32 v210, 0xffff0000, v134
	v_and_b32_e32 v211, 0xffff0000, v136
	v_pk_mul_f32 v[216:217], v[216:217], v[204:205]
	v_pk_mul_f32 v[218:219], v[218:219], v[206:207]
	v_pk_mul_f32 v[216:217], v[216:217], v[208:209]
	v_pk_mul_f32 v[218:219], v[218:219], v[210:211]
	v_lshlrev_b32_e32 v208, 16, v131
	v_lshlrev_b32_e32 v209, 16, v133
	v_lshlrev_b32_e32 v210, 16, v135
	v_lshlrev_b32_e32 v211, 16, v137
	v_pk_mul_f32 v[224:225], v[224:225], v[204:205]
	v_pk_mul_f32 v[226:227], v[226:227], v[206:207]
	v_pk_mul_f32 v[224:225], v[224:225], v[208:209]
	v_pk_mul_f32 v[226:227], v[226:227], v[210:211]
	v_and_b32_e32 v208, 0xffff0000, v131
	v_and_b32_e32 v209, 0xffff0000, v133
	v_and_b32_e32 v210, 0xffff0000, v135
	v_and_b32_e32 v211, 0xffff0000, v137
	v_pk_mul_f32 v[242:243], v[242:243], v[204:205]
	v_pk_mul_f32 v[244:245], v[244:245], v[206:207]
	v_pk_mul_f32 v[242:243], v[242:243], v[208:209]
	v_pk_mul_f32 v[244:245], v[244:245], v[210:211]
	v_cvt_pk_bf16_f32 v204, v212, v216
	v_cvt_pk_bf16_f32 v205, v224, v242
	v_cvt_pk_bf16_f32 v210, v213, v217
	v_cvt_pk_bf16_f32 v211, v225, v243
	v_cvt_pk_bf16_f32 v206, v214, v218
	v_cvt_pk_bf16_f32 v207, v226, v244
	v_cvt_pk_bf16_f32 v218, v215, v219
	v_cvt_pk_bf16_f32 v219, v227, v245
	v_and_b32_e32 v220, 1, v232
	v_mul_u32_u24_e32 v220, 0x7f8, v220
	v_add_u32_e32 v220, v189, v220
	s_mov_b32 vcc_lo, 0x55555555
	s_mov_b32 vcc_hi, 0x55555555
	v_cndmask_b32_dpp v208, v210, v204, vcc quad_perm:[1,0,3,2] row_mask:0xf bank_mask:0xf
	v_cndmask_b32_dpp v209, v211, v205, vcc quad_perm:[1,0,3,2] row_mask:0xf bank_mask:0xf
	v_cndmask_b32_dpp v216, v218, v206, vcc quad_perm:[1,0,3,2] row_mask:0xf bank_mask:0xf
	v_cndmask_b32_dpp v217, v219, v207, vcc quad_perm:[1,0,3,2] row_mask:0xf bank_mask:0xf
	s_not_b64 vcc, vcc
	v_cndmask_b32_dpp v210, v204, v210, vcc quad_perm:[1,0,3,2] row_mask:0xf bank_mask:0xf
	v_cndmask_b32_dpp v211, v205, v211, vcc quad_perm:[1,0,3,2] row_mask:0xf bank_mask:0xf
	v_cndmask_b32_dpp v218, v206, v218, vcc quad_perm:[1,0,3,2] row_mask:0xf bank_mask:0xf
	v_cndmask_b32_dpp v219, v207, v219, vcc quad_perm:[1,0,3,2] row_mask:0xf bank_mask:0xf
	global_store_dwordx4 v220, v[208:211], s[6:7]
	s_mov_b64 s[12:13], 0
	s_add_u32 s6, s3, 0x1600
	s_addc_u32 s7, s4, 0
	global_store_dwordx4 v220, v[216:219], s[6:7]
	s_add_u32 s6, s3, 0x1e00
	s_addc_u32 s7, s4, 0

; __device__ __forceinline__ bool scan_needfin(int s) { return s >= 0 && s < 35 && !scan_first(s + 1) && s + 1 != 20 && s + 1 != 2; }
;     ...
;     if (s == 21 || s == 3) asm volatile("s_waitcnt vmcnt(0)" ::: "memory");
;     else if (scan_needfin(s - 1)) { if (GDN) asm volatile("s_waitcnt vmcnt(14)" ::: "memory"); else asm volatile("s_waitcnt vmcnt(15)" ::: "memory"); }
;     else { if (GDN) asm volatile("s_waitcnt vmcnt(8)" ::: "memory"); else asm volatile("s_waitcnt vmcnt(9)" ::: "memory"); }
;     __syncthreads();
;     if (s > 0) {
;         const int sp = s - 1;
;         if (sp == 20 || sp == 2) { asm volatile("s_waitcnt vmcnt(0)" ::: "memory"); scan_fin_load<GDN>(F, b, h, dir, L, sp, PEND, fin); }
.LBB0_367:
.LBB0_368:
	s_cmp_eq_u32 s4, 3
	s_cselect_b64 s[12:13], -1, 0
	s_cmp_lg_u32 s4, 3
	s_cselect_b64 s[14:15], -1, 0

; __device__ __forceinline__ bool scan_needfin(int s) { return s >= 0 && s < 35 && !scan_first(s + 1) && s + 1 != 20 && s + 1 != 2; }
;     ...
;     if (s == 21 || s == 3) asm volatile("s_waitcnt vmcnt(0)" ::: "memory");
;     else if (scan_needfin(s - 1)) { if (GDN) asm volatile("s_waitcnt vmcnt(14)" ::: "memory"); else asm volatile("s_waitcnt vmcnt(15)" ::: "memory"); }
;     else { if (GDN) asm volatile("s_waitcnt vmcnt(8)" ::: "memory"); else asm volatile("s_waitcnt vmcnt(9)" ::: "memory"); }
;     __syncthreads();
;     if (s > 0) {
;         const int sp = s - 1;
;         if (sp == 20 || sp == 2) { asm volatile("s_waitcnt vmcnt(0)" ::: "memory"); scan_fin_load<GDN>(F, b, h, dir, L, sp, PEND, fin); }
.LBB0_379:
.LBB0_380:
	s_cmp_eq_u32 s4, 3
	s_cselect_b64 s[18:19], -1, 0
	s_cmp_lg_u32 s4, 3
	s_cselect_b64 s[12:13], -1, 0

; __device__ __forceinline__ float row16_sum(float v) { v += dppf<0xB1>(v); v += dppf<0x4E>(v); v += dppf<0x141>(v); v += dppf<0x140>(v); return v; }
; __device__ __forceinline__ float frsq(float x) { return __builtin_amdgcn_rsqf(x); }
; __device__ __forceinline__ v2u pack4(const f32x4 v) { v2u r; r.x = pk2(v[0], v[1]); r.y = pk2(v[2], v[3]); return r; }
; __device__ __forceinline__ f32x4 unpack4(const v2u w) { f32x4 r; r[0] = bflo(w.x); r[1] = bfhi(w.x); r[2] = bflo(w.y); r[3] = bfhi(w.y); return r; }
; __device__ __forceinline__ const char* upin(const char* p) { asm volatile("" : "+s"(p)); return p; }
; __device__ __forceinline__ char* upin(char* p) { asm volatile("" : "+s"(p)); return p; }
; template <bool GDN> __device__ __forceinline__ void scan_finish(const Frame& F, int b, int h, int dir, const ScanLane& L, int s, float* PEND, const f32x4 (&Oin)[4], const ScanFin& f) {
;     ...
;         f32x4 O[4]; float ss[4] = {0.f, 0.f, 0.f, 0.f};
; #pragma unroll
;         for (int t = 0; t < 4; ++t)
;             { const f32x4 pv = unpack4(f.pend[t]);
; #pragma unroll
;             for (int i = 0; i < 4; ++i) { O[t][i] = Oin[t][i] + pv[i]; ss[i] += O[t][i] * O[t][i]; } }
; #pragma unroll
;         for (int i = 0; i < 4; ++i) ss[i] = frsq(row16_sum(ss[i]) * (1.f / 64.f) + EPS);
;         char* mp = (char*)F.MIX + ((size_t)row0 * 1024 + (GDN ? 0 : 768) + h * 64) * 2;
; #pragma unroll
;         for (int i = 0; i < 4; ++i) { const f32x4 g = unpack4(f.gz[i]); f32x4 ov;
; #pragma unroll
;             for (int t = 0; t < 4; ++t) ov[t] = O[t][i] * ss[i] * g[t];
;             stu<v2u>(upin(mp + i * 2048), L.mix, pack4(ov)); }
.LBB0_385:
	s_cmp_gt_u32 s25, 3
	s_cselect_b32 s5, 39, 3
	s_add_i32 s5, s5, s24
	s_add_i32 s1, s5, 3
	s_and_b64 s[6:7], s[90:91], exec
	s_cselect_b32 s1, s25, s1
	s_cmp_lt_u32 s4, 5
	s_cselect_b32 s3, 2, 20
	s_cmp_lt_u32 s25, s3
	s_mov_b64 s[12:13], -1
	s_cbranch_scc1 .LBB0_387
	s_lshl_b32 s3, s1, 6
	s_cmp_lt_i32 s1, 4
	s_cselect_b32 s6, s63, s33
	s_add_i32 s6, s6, s3
	s_ashr_i32 s7, s6, 31
	s_lshl_b64 s[6:7], s[6:7], 11
	s_add_u32 s3, s26, s6
	s_addc_u32 s6, s27, s7
	s_add_u32 s8, s3, 0x600
	s_addc_u32 s9, s6, 0
	v_lshlrev_b32_e32 v208, 16, v4
	v_and_b32_e32 v209, 0xffff0000, v4
	v_lshlrev_b32_e32 v210, 16, v5
	v_and_b32_e32 v211, 0xffff0000, v5
	v_pk_add_f32 v[212:213], v[104:105], v[208:209]
	v_pk_add_f32 v[214:215], v[106:107], v[210:211]
	v_pk_mul_f32 v[204:205], v[212:213], v[212:213]
	v_pk_mul_f32 v[206:207], v[214:215], v[214:215]
	v_lshlrev_b32_e32 v208, 16, v6
	v_and_b32_e32 v209, 0xffff0000, v6
	v_lshlrev_b32_e32 v210, 16, v7
	v_and_b32_e32 v211, 0xffff0000, v7
	v_pk_add_f32 v[216:217], v[108:109], v[208:209]
	v_pk_add_f32 v[218:219], v[110:111], v[210:211]
	v_pk_fma_f32 v[204:205], v[216:217], v[216:217], v[204:205]
	v_pk_fma_f32 v[206:207], v[218:219], v[218:219], v[206:207]
	v_lshlrev_b32_e32 v208, 16, v8
	v_and_b32_e32 v209, 0xffff0000, v8
	v_lshlrev_b32_e32 v210, 16, v9
	v_and_b32_e32 v211, 0xffff0000, v9
	v_pk_add_f32 v[224:225], v[112:113], v[208:209]
	v_pk_add_f32 v[226:227], v[114:115], v[210:211]
	v_pk_fma_f32 v[204:205], v[224:225], v[224:225], v[204:205]
	v_pk_fma_f32 v[206:207], v[226:227], v[226:227], v[206:207]
	v_lshlrev_b32_e32 v208, 16, v10
	v_and_b32_e32 v209, 0xffff0000, v10
	v_lshlrev_b32_e32 v210, 16, v11
	v_and_b32_e32 v211, 0xffff0000, v11
	v_pk_add_f32 v[242:243], v[116:117], v[208:209]
	v_pk_add_f32 v[244:245], v[118:119], v[210:211]
	v_pk_fma_f32 v[204:205], v[242:243], v[242:243], v[204:205]
	v_pk_fma_f32 v[206:207], v[244:245], v[244:245], v[206:207]
	s_nop 1
	v_add_f32_dpp v204, v204, v204 quad_perm:[1,0,3,2] row_mask:0xf bank_mask:0xf bound_ctrl:1
	v_add_f32_dpp v205, v205, v205 quad_perm:[1,0,3,2] row_mask:0xf bank_mask:0xf bound_ctrl:1
	v_add_f32_dpp v206, v206, v206 quad_perm:[1,0,3,2] row_mask:0xf bank_mask:0xf bound_ctrl:1
	v_add_f32_dpp v207, v207, v207 quad_perm:[1,0,3,2] row_mask:0xf bank_mask:0xf bound_ctrl:1
	v_add_f32_dpp v204, v204, v204 quad_perm:[2,3,0,1] row_mask:0xf bank_mask:0xf bound_ctrl:1
	v_add_f32_dpp v205, v205, v205 quad_perm:[2,3,0,1] row_mask:0xf bank_mask:0xf bound_ctrl:1
	v_add_f32_dpp v206, v206, v206 quad_perm:[2,3,0,1] row_mask:0xf bank_mask:0xf bound_ctrl:1
	v_add_f32_dpp v207, v207, v207 quad_perm:[2,3,0,1] row_mask:0xf bank_mask:0xf bound_ctrl:1
	v_add_f32_dpp v204, v204, v204 row_half_mirror row_mask:0xf bank_mask:0xf bound_ctrl:1
	v_add_f32_dpp v205, v205, v205 row_half_mirror row_mask:0xf bank_mask:0xf bound_ctrl:1
	v_add_f32_dpp v206, v206, v206 row_half_mirror row_mask:0xf bank_mask:0xf bound_ctrl:1
	v_add_f32_dpp v207, v207, v207 row_half_mirror row_mask:0xf bank_mask:0xf bound_ctrl:1
	v_add_f32_dpp v204, v204, v204 row_mirror row_mask:0xf bank_mask:0xf bound_ctrl:1
	v_add_f32_dpp v205, v205, v205 row_mirror row_mask:0xf bank_mask:0xf bound_ctrl:1
	v_add_f32_dpp v206, v206, v206 row_mirror row_mask:0xf bank_mask:0xf bound_ctrl:1
	v_add_f32_dpp v207, v207, v207 row_mirror row_mask:0xf bank_mask:0xf bound_ctrl:1
	v_fmamk_f32 v204, v204, 0x3c800000, v231
	v_fmamk_f32 v205, v205, 0x3c800000, v231
	v_fmamk_f32 v206, v206, 0x3c800000, v231
	v_fmamk_f32 v207, v207, 0x3c800000, v231
	v_rsq_f32_e32 v204, v204
	v_rsq_f32_e32 v205, v205
	v_rsq_f32_e32 v206, v206
	v_rsq_f32_e32 v207, v207
	v_lshlrev_b32_e32 v208, 16, v122
	v_lshlrev_b32_e32 v209, 16, v124
	v_lshlrev_b32_e32 v210, 16, v126
	v_lshlrev_b32_e32 v211, 16, v128
	v_pk_mul_f32 v[212:213], v[212:213], v[204:205]
	v_pk_mul_f32 v[214:215], v[214:215], v[206:207]
	v_pk_mul_f32 v[212:213], v[212:213], v[208:209]
	v_pk_mul_f32 v[214:215], v[214:215], v[210:211]
	v_and_b32_e32 v208, 0xffff0000, v122
	v_and_b32_e32 v209, 0xffff0000, v124
	v_and_b32_e32 v210, 0xffff0000, v126
	v_and_b32_e32 v211, 0xffff0000, v128
	v_pk_mul_f32 v[216:217], v[216:217], v[204:205]
	v_pk_mul_f32 v[218:219], v[218:219], v[206:207]
	v_pk_mul_f32 v[216:217], v[216:217], v[208:209]
	v_pk_mul_f32 v[218:219], v[218:219], v[210:211]
	v_lshlrev_b32_e32 v208, 16, v123
	v_lshlrev_b32_e32 v209, 16, v125
	v_lshlrev_b32_e32 v210, 16, v127
	v_lshlrev_b32_e32 v211, 16, v129
	v_pk_mul_f32 v[224:225], v[224:225], v[204:205]
	v_pk_mul_f32 v[226:227], v[226:227], v[206:207]
	v_pk_mul_f32 v[224:225], v[224:225], v[208:209]
	v_pk_mul_f32 v[226:227], v[226:227], v[210:211]
	v_and_b32_e32 v208, 0xffff0000, v123
	v_and_b32_e32 v209, 0xffff0000, v125
	v_and_b32_e32 v210, 0xffff0000, v127
	v_and_b32_e32 v211, 0xffff0000, v129
	v_pk_mul_f32 v[242:243], v[242:243], v[204:205]
	v_pk_mul_f32 v[244:245], v[244:245], v[206:207]
	v_pk_mul_f32 v[242:243], v[242:243], v[208:209]
	v_pk_mul_f32 v[244:245], v[244:245], v[210:211]
	v_cvt_pk_bf16_f32 v204, v212, v216
	v_cvt_pk_bf16_f32 v205, v224, v242
	v_cvt_pk_bf16_f32 v210, v213, v217
	v_cvt_pk_bf16_f32 v211, v225, v243
	v_cvt_pk_bf16_f32 v206, v214, v218
	v_cvt_pk_bf16_f32 v207, v226, v244
	v_cvt_pk_bf16_f32 v218, v215, v219
	v_cvt_pk_bf16_f32 v219, v227, v245
	v_and_b32_e32 v220, 1, v232
	v_mul_u32_u24_e32 v220, 0x7f8, v220
	v_add_u32_e32 v220, v39, v220
	s_mov_b32 vcc_lo, 0x55555555
	s_mov_b32 vcc_hi, 0x55555555
	v_cndmask_b32_dpp v208, v210, v204, vcc quad_perm:[1,0,3,2] row_mask:0xf bank_mask:0xf
	v_cndmask_b32_dpp v209, v211, v205, vcc quad_perm:[1,0,3,2] row_mask:0xf bank_mask:0xf
	v_cndmask_b32_dpp v216, v218, v206, vcc quad_perm:[1,0,3,2] row_mask:0xf bank_mask:0xf
	v_cndmask_b32_dpp v217, v219, v207, vcc quad_perm:[1,0,3,2] row_mask:0xf bank_mask:0xf
	s_not_b64 vcc, vcc
	v_cndmask_b32_dpp v210, v204, v210, vcc quad_perm:[1,0,3,2] row_mask:0xf bank_mask:0xf
	v_cndmask_b32_dpp v211, v205, v211, vcc quad_perm:[1,0,3,2] row_mask:0xf bank_mask:0xf
	v_cndmask_b32_dpp v218, v206, v218, vcc quad_perm:[1,0,3,2] row_mask:0xf bank_mask:0xf
	v_cndmask_b32_dpp v219, v207, v219, vcc quad_perm:[1,0,3,2] row_mask:0xf bank_mask:0xf
	global_store_dwordx4 v220, v[208:211], s[8:9]
	s_mov_b64 s[12:13], 0
	s_add_u32 s8, s3, 0x1600
	s_addc_u32 s9, s6, 0
	global_store_dwordx4 v220, v[216:219], s[8:9]

; __device__ __forceinline__ bool scan_needfin(int s) { return s >= 0 && s < 35 && !scan_first(s + 1) && s + 1 != 20 && s + 1 != 2; }
;     ...
;     if (s > 0) {
;         const int sp = s - 1;
;         if (sp == 20 || sp == 2) { asm volatile("s_waitcnt vmcnt(0)" ::: "memory"); scan_fin_load<GDN>(F, b, h, dir, L, sp, PEND, fin); }
;         if (!nofin) scan_finish<GDN>(F, b, h, dir, L, sp, PEND, Oprev, fin);
;     }
;     if (s == 36) return false;
;     if (scan_needfin(s) && ko != 1 && ko != 3) scan_fin_load<GDN>(F, b, h, dir, L, s + 1, PEND, fin);
.LBB0_392:
.LBB0_393:
	s_cmp_lg_u32 s4, 1
	s_cselect_b64 s[12:13], -1, 0

; template <int N> __device__ __forceinline__ float row16_bcast(float v) { return dppf<0x150 + N>(v); }
; __device__ __forceinline__ float frcp(float x) { return __builtin_amdgcn_rcpf(x); }
;     ...
;             S[t] = S[t] * gl + bv; O[t] = o * use.wi + ov; }
;     }
;     if (!GDN) {
; #pragma unroll
;         for (int i = 0; i < 4; ++i) { const float den = row16_bcast<0>(O[NT - 1][i]), fl = row16_bcast<1>(O[NT - 1][i]); const float dv = frcp(fmaxf(fabsf(den), fl));
; #pragma unroll
;             for (int t = 0; t < 4; ++t) O[t][i] *= dv; }
;     }
.LBB0_402:
	v_lshlrev_b32_e32 v168, 16, v53
	v_and_b32_e32 v169, 0xffff0000, v53
	v_pk_fma_f32 v[168:169], v[102:103], v[106:107], v[168:169]
	v_lshlrev_b32_e32 v106, 16, v55
	v_and_b32_e32 v107, 0xffff0000, v55
	v_pk_fma_f32 v[170:171], v[102:103], v[110:111], v[106:107]
	v_lshlrev_b32_e32 v106, 16, v33
	v_and_b32_e32 v107, 0xffff0000, v33
	v_pk_fma_f32 v[172:173], v[102:103], v[114:115], v[106:107]
	v_lshlrev_b32_e32 v106, 16, v35
	v_and_b32_e32 v107, 0xffff0000, v35
	v_pk_fma_f32 v[174:175], v[102:103], v[118:119], v[106:107]
	v_lshlrev_b32_e32 v166, 16, v52
	v_and_b32_e32 v167, 0xffff0000, v52
	v_max_f32_e64 v106, |v187|, v193
	v_pk_fma_f32 v[166:167], v[100:101], v[104:105], v[166:167]
	v_lshlrev_b32_e32 v104, 16, v54
	v_and_b32_e32 v105, 0xffff0000, v54
	v_rcp_f32_e32 v106, v106
	v_pk_fma_f32 v[108:109], v[100:101], v[108:109], v[104:105]
	v_lshlrev_b32_e32 v104, 16, v32
	v_and_b32_e32 v105, 0xffff0000, v32
	v_pk_fma_f32 v[110:111], v[100:101], v[112:113], v[104:105]
	v_lshlrev_b32_e32 v104, 16, v34
	v_and_b32_e32 v105, 0xffff0000, v34
	v_pk_fma_f32 v[114:115], v[100:101], v[116:117], v[104:105]
	v_mov_b32_e32 v104, v166
	v_mov_b32_e32 v105, v108
	v_pk_mul_f32 v[104:105], v[104:105], v[106:107] op_sel_hi:[1,0]
	v_max_f32_e64 v107, |v179|, v186
	v_mov_b32_e32 v112, v110
	v_rcp_f32_e32 v110, v107
	v_mov_b32_e32 v113, v114
	v_mov_b32_e32 v108, v167
	v_pk_mul_f32 v[106:107], v[112:113], v[106:107] op_sel_hi:[1,0]
	v_pk_mul_f32 v[112:113], v[108:109], v[110:111] op_sel_hi:[1,0]
	v_max_f32_e64 v108, |v165|, v178
	v_rcp_f32_e32 v116, v108
	v_mov_b32_e32 v114, v111
	v_mov_b32_e32 v108, v168
	v_mov_b32_e32 v109, v170
	v_pk_mul_f32 v[114:115], v[114:115], v[110:111] op_sel_hi:[1,0]
	v_pk_mul_f32 v[108:109], v[108:109], v[116:117] op_sel_hi:[1,0]
	v_max_f32_e64 v111, |v163|, v164
	v_rcp_f32_e32 v164, v111
	s_cmp_gt_u32 s25, 2
	v_mov_b32_e32 v110, v172
	v_mov_b32_e32 v111, v174
	v_mov_b32_e32 v170, v169
	v_mov_b32_e32 v174, v173
	s_cselect_b32 s6, 20, 2
	v_pk_mul_f32 v[110:111], v[110:111], v[116:117] op_sel_hi:[1,0]
	v_pk_mul_f32 v[118:119], v[170:171], v[164:165] op_sel_hi:[1,0]
	v_pk_mul_f32 v[116:117], v[174:175], v[164:165] op_sel_hi:[1,0]
	s_cmp_lt_u32 s4, s6
	s_mov_b64 s[10:11], -1
	s_waitcnt lgkmcnt(0)
	s_barrier
	s_cbranch_scc1 .LBB0_410
; __device__ __forceinline__ float row16_sum(float v) { v += dppf<0xB1>(v); v += dppf<0x4E>(v); v += dppf<0x141>(v); v += dppf<0x140>(v); return v; }
; __device__ __forceinline__ float frsq(float x) { return __builtin_amdgcn_rsqf(x); }
; __device__ __forceinline__ v2u pack4(const f32x4 v) { v2u r; r.x = pk2(v[0], v[1]); r.y = pk2(v[2], v[3]); return r; }
; __device__ __forceinline__ f32x4 unpack4(const v2u w) { f32x4 r; r[0] = bflo(w.x); r[1] = bfhi(w.x); r[2] = bflo(w.y); r[3] = bfhi(w.y); return r; }
; __device__ __forceinline__ const char* upin(const char* p) { asm volatile("" : "+s"(p)); return p; }
; __device__ __forceinline__ char* upin(char* p) { asm volatile("" : "+s"(p)); return p; }
; template <bool GDN> __device__ __forceinline__ void scan_finish(const Frame& F, int b, int h, int dir, const ScanLane& L, int s, float* PEND, const f32x4 (&Oin)[4], const ScanFin& f) {
;     ...
;         f32x4 O[4]; float ss[4] = {0.f, 0.f, 0.f, 0.f};
; #pragma unroll
;         for (int t = 0; t < 4; ++t)
;             { const f32x4 pv = unpack4(f.pend[t]);
; #pragma unroll
;             for (int i = 0; i < 4; ++i) { O[t][i] = Oin[t][i] + pv[i]; ss[i] += O[t][i] * O[t][i]; } }
; #pragma unroll
;         for (int i = 0; i < 4; ++i) ss[i] = frsq(row16_sum(ss[i]) * (1.f / 64.f) + EPS);
;         char* mp = (char*)F.MIX + ((size_t)row0 * 1024 + (GDN ? 0 : 768) + h * 64) * 2;
; #pragma unroll
;         for (int i = 0; i < 4; ++i) { const f32x4 g = unpack4(f.gz[i]); f32x4 ov;
; #pragma unroll
;             for (int t = 0; t < 4; ++t) ov[t] = O[t][i] * ss[i] * g[t];
;             stu<v2u>(upin(mp + i * 2048), L.mix, pack4(ov)); }
	s_lshl_b32 s4, s5, 6
	s_cmp_lt_i32 s5, 4
	s_cselect_b32 s6, s63, s33
	s_add_i32 s6, s6, s4
	s_ashr_i32 s7, s6, 31
	s_lshl_b64 s[6:7], s[6:7], 11
	s_add_u32 s4, s26, s6
	s_addc_u32 s8, s27, s7
	s_add_u32 s6, s4, 0x600
	s_addc_u32 s7, s8, 0
	v_lshlrev_b32_e32 v246, 16, v12
	v_lshlrev_b32_e32 v247, 16, v14
	v_lshlrev_b32_e32 v220, 16, v16
	v_lshlrev_b32_e32 v221, 16, v18
	v_pk_add_f32 v[212:213], v[104:105], v[246:247]
	v_pk_add_f32 v[214:215], v[106:107], v[220:221]
	v_pk_mul_f32 v[204:205], v[212:213], v[212:213]
	v_pk_fma_f32 v[204:205], v[214:215], v[214:215], v[204:205]
	v_and_b32_e32 v246, 0xffff0000, v12
	v_and_b32_e32 v247, 0xffff0000, v14
	v_and_b32_e32 v220, 0xffff0000, v16
	v_and_b32_e32 v221, 0xffff0000, v18
	v_pk_add_f32 v[216:217], v[112:113], v[246:247]
	v_pk_add_f32 v[218:219], v[114:115], v[220:221]
	v_pk_mul_f32 v[206:207], v[216:217], v[216:217]
	v_pk_fma_f32 v[206:207], v[218:219], v[218:219], v[206:207]
	v_lshlrev_b32_e32 v246, 16, v13
	v_lshlrev_b32_e32 v247, 16, v15
	v_lshlrev_b32_e32 v220, 16, v17
	v_lshlrev_b32_e32 v221, 16, v19
	v_pk_add_f32 v[224:225], v[108:109], v[246:247]
	v_pk_add_f32 v[226:227], v[110:111], v[220:221]
	v_pk_mul_f32 v[208:209], v[224:225], v[224:225]
	v_pk_fma_f32 v[208:209], v[226:227], v[226:227], v[208:209]
	v_and_b32_e32 v246, 0xffff0000, v13
	v_and_b32_e32 v247, 0xffff0000, v15
	v_and_b32_e32 v220, 0xffff0000, v17
	v_and_b32_e32 v221, 0xffff0000, v19
	v_pk_add_f32 v[242:243], v[118:119], v[246:247]
	v_pk_add_f32 v[244:245], v[116:117], v[220:221]
	v_pk_mul_f32 v[210:211], v[242:243], v[242:243]
	v_pk_fma_f32 v[210:211], v[244:245], v[244:245], v[210:211]
	v_add_f32_e32 v204, v204, v205
	v_add_f32_e32 v206, v206, v207
	v_add_f32_e32 v208, v208, v209
	v_add_f32_e32 v210, v210, v211
	s_nop 0
	v_add_f32_dpp v204, v204, v204 quad_perm:[1,0,3,2] row_mask:0xf bank_mask:0xf bound_ctrl:1
	v_add_f32_dpp v206, v206, v206 quad_perm:[1,0,3,2] row_mask:0xf bank_mask:0xf bound_ctrl:1
	v_add_f32_dpp v208, v208, v208 quad_perm:[1,0,3,2] row_mask:0xf bank_mask:0xf bound_ctrl:1
	v_add_f32_dpp v210, v210, v210 quad_perm:[1,0,3,2] row_mask:0xf bank_mask:0xf bound_ctrl:1
	v_add_f32_dpp v204, v204, v204 quad_perm:[2,3,0,1] row_mask:0xf bank_mask:0xf bound_ctrl:1
	v_add_f32_dpp v206, v206, v206 quad_perm:[2,3,0,1] row_mask:0xf bank_mask:0xf bound_ctrl:1
	v_add_f32_dpp v208, v208, v208 quad_perm:[2,3,0,1] row_mask:0xf bank_mask:0xf bound_ctrl:1
	v_add_f32_dpp v210, v210, v210 quad_perm:[2,3,0,1] row_mask:0xf bank_mask:0xf bound_ctrl:1
	v_add_f32_dpp v204, v204, v204 row_half_mirror row_mask:0xf bank_mask:0xf bound_ctrl:1
	v_add_f32_dpp v206, v206, v206 row_half_mirror row_mask:0xf bank_mask:0xf bound_ctrl:1
	v_add_f32_dpp v208, v208, v208 row_half_mirror row_mask:0xf bank_mask:0xf bound_ctrl:1
	v_add_f32_dpp v210, v210, v210 row_half_mirror row_mask:0xf bank_mask:0xf bound_ctrl:1
	v_add_f32_dpp v204, v204, v204 row_mirror row_mask:0xf bank_mask:0xf bound_ctrl:1
	v_add_f32_dpp v206, v206, v206 row_mirror row_mask:0xf bank_mask:0xf bound_ctrl:1
	v_add_f32_dpp v208, v208, v208 row_mirror row_mask:0xf bank_mask:0xf bound_ctrl:1
	v_add_f32_dpp v210, v210, v210 row_mirror row_mask:0xf bank_mask:0xf bound_ctrl:1
	v_fmamk_f32 v204, v204, 0x3c800000, v231
	v_fmamk_f32 v206, v206, 0x3c800000, v231
	v_fmamk_f32 v208, v208, 0x3c800000, v231
	v_fmamk_f32 v210, v210, 0x3c800000, v231
	v_rsq_f32_e32 v204, v204
	v_rsq_f32_e32 v206, v206
	v_rsq_f32_e32 v208, v208
	v_rsq_f32_e32 v210, v210
	v_lshlrev_b32_e32 v246, 16, v130
	v_and_b32_e32 v247, 0xffff0000, v130
	v_lshlrev_b32_e32 v220, 16, v131
	v_and_b32_e32 v221, 0xffff0000, v131
	v_pk_mul_f32 v[212:213], v[212:213], v[204:205] op_sel_hi:[1,0]
	v_pk_mul_f32 v[214:215], v[214:215], v[204:205] op_sel_hi:[1,0]
	v_pk_mul_f32 v[212:213], v[212:213], v[246:247]
	v_pk_mul_f32 v[214:215], v[214:215], v[220:221]
	v_lshlrev_b32_e32 v246, 16, v132
	v_and_b32_e32 v247, 0xffff0000, v132
	v_lshlrev_b32_e32 v220, 16, v133
	v_and_b32_e32 v221, 0xffff0000, v133
	v_pk_mul_f32 v[216:217], v[216:217], v[206:207] op_sel_hi:[1,0]
	v_pk_mul_f32 v[218:219], v[218:219], v[206:207] op_sel_hi:[1,0]
	v_pk_mul_f32 v[216:217], v[216:217], v[246:247]
	v_pk_mul_f32 v[218:219], v[218:219], v[220:221]
	v_lshlrev_b32_e32 v246, 16, v134
	v_and_b32_e32 v247, 0xffff0000, v134
	v_lshlrev_b32_e32 v220, 16, v135
	v_and_b32_e32 v221, 0xffff0000, v135
	v_pk_mul_f32 v[224:225], v[224:225], v[208:209] op_sel_hi:[1,0]
	v_pk_mul_f32 v[226:227], v[226:227], v[208:209] op_sel_hi:[1,0]
	v_pk_mul_f32 v[224:225], v[224:225], v[246:247]
	v_pk_mul_f32 v[226:227], v[226:227], v[220:221]
	v_lshlrev_b32_e32 v246, 16, v136
	v_and_b32_e32 v247, 0xffff0000, v136
	v_lshlrev_b32_e32 v220, 16, v137
	v_and_b32_e32 v221, 0xffff0000, v137
	v_pk_mul_f32 v[242:243], v[242:243], v[210:211] op_sel_hi:[1,0]
	v_pk_mul_f32 v[244:245], v[244:245], v[210:211] op_sel_hi:[1,0]
	v_pk_mul_f32 v[242:243], v[242:243], v[246:247]
	v_pk_mul_f32 v[244:245], v[244:245], v[220:221]
	v_cvt_pk_bf16_f32 v204, v212, v213
	v_cvt_pk_bf16_f32 v205, v214, v215
	v_cvt_pk_bf16_f32 v210, v216, v217
	v_cvt_pk_bf16_f32 v211, v218, v219
	v_cvt_pk_bf16_f32 v206, v224, v225
	v_cvt_pk_bf16_f32 v207, v226, v227
	v_cvt_pk_bf16_f32 v218, v242, v243
	v_cvt_pk_bf16_f32 v219, v244, v245
	v_and_b32_e32 v220, 1, v232
	v_mul_u32_u24_e32 v220, 0x7f8, v220
	v_add_u32_e32 v220, v162, v220
	s_mov_b32 vcc_lo, 0x55555555
	s_mov_b32 vcc_hi, 0x55555555
	v_cndmask_b32_dpp v208, v210, v204, vcc quad_perm:[1,0,3,2] row_mask:0xf bank_mask:0xf
	v_cndmask_b32_dpp v209, v211, v205, vcc quad_perm:[1,0,3,2] row_mask:0xf bank_mask:0xf
	v_cndmask_b32_dpp v216, v218, v206, vcc quad_perm:[1,0,3,2] row_mask:0xf bank_mask:0xf
	v_cndmask_b32_dpp v217, v219, v207, vcc quad_perm:[1,0,3,2] row_mask:0xf bank_mask:0xf
	s_not_b64 vcc, vcc
	v_cndmask_b32_dpp v210, v204, v210, vcc quad_perm:[1,0,3,2] row_mask:0xf bank_mask:0xf
	v_cndmask_b32_dpp v211, v205, v211, vcc quad_perm:[1,0,3,2] row_mask:0xf bank_mask:0xf
	v_cndmask_b32_dpp v218, v206, v218, vcc quad_perm:[1,0,3,2] row_mask:0xf bank_mask:0xf
	v_cndmask_b32_dpp v219, v207, v219, vcc quad_perm:[1,0,3,2] row_mask:0xf bank_mask:0xf
	global_store_dwordx4 v220, v[208:211], s[6:7]
	s_add_u32 s6, s4, 0x1600
	s_addc_u32 s7, s8, 0
	global_store_dwordx4 v220, v[216:219], s[6:7]
	s_add_u32 s6, s4, 0x1e00
	s_addc_u32 s7, s8, 0
	s_cbranch_execz .LBB0_411

;     ...
;     if (s > 0) {
;         const int sp = s - 1;
;         if (sp == 20 || sp == 2) { asm volatile("s_waitcnt vmcnt(0)" ::: "memory"); scan_fin_load<GDN>(F, b, h, dir, L, sp, PEND, fin); }
;         if (!nofin) scan_finish<GDN>(F, b, h, dir, L, sp, PEND, Oprev, fin);
.LBB0_417:
.LBB0_418:
	s_cmp_eq_u32 s25, 0
	s_cselect_b64 s[10:11], -1, 0
	s_cmp_lg_u32 s25, 0
	s_cselect_b64 s[12:13], -1, 0

; __device__ __forceinline__ float row16_sum(float v) { v += dppf<0xB1>(v); v += dppf<0x4E>(v); v += dppf<0x141>(v); v += dppf<0x140>(v); return v; }
; __device__ __forceinline__ float frsq(float x) { return __builtin_amdgcn_rsqf(x); }
; __device__ __forceinline__ v2u pack4(const f32x4 v) { v2u r; r.x = pk2(v[0], v[1]); r.y = pk2(v[2], v[3]); return r; }
; __device__ __forceinline__ f32x4 unpack4(const v2u w) { f32x4 r; r[0] = bflo(w.x); r[1] = bfhi(w.x); r[2] = bflo(w.y); r[3] = bfhi(w.y); return r; }
; __device__ __forceinline__ const char* upin(const char* p) { asm volatile("" : "+s"(p)); return p; }
; __device__ __forceinline__ char* upin(char* p) { asm volatile("" : "+s"(p)); return p; }
; template <bool GDN> __device__ __forceinline__ void scan_finish(const Frame& F, int b, int h, int dir, const ScanLane& L, int s, float* PEND, const f32x4 (&Oin)[4], const ScanFin& f) {
;     ...
;         f32x4 O[4]; float ss[4] = {0.f, 0.f, 0.f, 0.f};
; #pragma unroll
;         for (int t = 0; t < 4; ++t)
;             { const f32x4 pv = unpack4(f.pend[t]);
; #pragma unroll
;             for (int i = 0; i < 4; ++i) { O[t][i] = Oin[t][i] + pv[i]; ss[i] += O[t][i] * O[t][i]; } }
; #pragma unroll
;         for (int i = 0; i < 4; ++i) ss[i] = frsq(row16_sum(ss[i]) * (1.f / 64.f) + EPS);
;         char* mp = (char*)F.MIX + ((size_t)row0 * 1024 + (GDN ? 0 : 768) + h * 64) * 2;
; #pragma unroll
;         for (int i = 0; i < 4; ++i) { const f32x4 g = unpack4(f.gz[i]); f32x4 ov;
; #pragma unroll
;             for (int t = 0; t < 4; ++t) ov[t] = O[t][i] * ss[i] * g[t];
;             stu<v2u>(upin(mp + i * 2048), L.mix, pack4(ov)); }
.LBB0_434:
	s_lshl_b32 s3, s4, 6
	s_cmp_lt_i32 s4, 4
	s_cselect_b32 s5, s63, s33
	s_add_i32 s6, s5, s3
	s_ashr_i32 s7, s6, 31
	s_lshl_b64 s[6:7], s[6:7], 11
	s_add_u32 s3, s26, s6
	s_addc_u32 s5, s27, s7
	s_add_u32 s6, s3, 0x600
	s_addc_u32 s7, s5, 0
	v_lshlrev_b32_e32 v208, 16, v4
	v_and_b32_e32 v209, 0xffff0000, v4
	v_lshlrev_b32_e32 v210, 16, v5
	v_and_b32_e32 v211, 0xffff0000, v5
	v_pk_add_f32 v[212:213], v[50:51], v[208:209]
	v_pk_add_f32 v[214:215], v[2:3], v[210:211]
	v_pk_mul_f32 v[204:205], v[212:213], v[212:213]
	v_pk_mul_f32 v[206:207], v[214:215], v[214:215]
	v_lshlrev_b32_e32 v208, 16, v6
	v_and_b32_e32 v209, 0xffff0000, v6
	v_lshlrev_b32_e32 v210, 16, v7
	v_and_b32_e32 v211, 0xffff0000, v7
	v_pk_add_f32 v[216:217], v[112:113], v[208:209]
	v_pk_add_f32 v[218:219], v[118:119], v[210:211]
	v_pk_fma_f32 v[204:205], v[216:217], v[216:217], v[204:205]
	v_pk_fma_f32 v[206:207], v[218:219], v[218:219], v[206:207]
	v_lshlrev_b32_e32 v208, 16, v8
	v_and_b32_e32 v209, 0xffff0000, v8
	v_lshlrev_b32_e32 v210, 16, v9
	v_and_b32_e32 v211, 0xffff0000, v9
	v_pk_add_f32 v[224:225], v[56:57], v[208:209]
	v_pk_add_f32 v[226:227], v[48:49], v[210:211]
	v_pk_fma_f32 v[204:205], v[224:225], v[224:225], v[204:205]
	v_pk_fma_f32 v[206:207], v[226:227], v[226:227], v[206:207]
	v_lshlrev_b32_e32 v208, 16, v10
	v_and_b32_e32 v209, 0xffff0000, v10
	v_lshlrev_b32_e32 v210, 16, v11
	v_and_b32_e32 v211, 0xffff0000, v11
	v_pk_add_f32 v[242:243], v[114:115], v[208:209]
	v_pk_add_f32 v[244:245], v[116:117], v[210:211]
	v_pk_fma_f32 v[204:205], v[242:243], v[242:243], v[204:205]
	v_pk_fma_f32 v[206:207], v[244:245], v[244:245], v[206:207]
	s_nop 1
	v_add_f32_dpp v204, v204, v204 quad_perm:[1,0,3,2] row_mask:0xf bank_mask:0xf bound_ctrl:1
	v_add_f32_dpp v205, v205, v205 quad_perm:[1,0,3,2] row_mask:0xf bank_mask:0xf bound_ctrl:1
	v_add_f32_dpp v206, v206, v206 quad_perm:[1,0,3,2] row_mask:0xf bank_mask:0xf bound_ctrl:1
	v_add_f32_dpp v207, v207, v207 quad_perm:[1,0,3,2] row_mask:0xf bank_mask:0xf bound_ctrl:1
	v_add_f32_dpp v204, v204, v204 quad_perm:[2,3,0,1] row_mask:0xf bank_mask:0xf bound_ctrl:1
	v_add_f32_dpp v205, v205, v205 quad_perm:[2,3,0,1] row_mask:0xf bank_mask:0xf bound_ctrl:1
	v_add_f32_dpp v206, v206, v206 quad_perm:[2,3,0,1] row_mask:0xf bank_mask:0xf bound_ctrl:1
	v_add_f32_dpp v207, v207, v207 quad_perm:[2,3,0,1] row_mask:0xf bank_mask:0xf bound_ctrl:1
	v_add_f32_dpp v204, v204, v204 row_half_mirror row_mask:0xf bank_mask:0xf bound_ctrl:1
	v_add_f32_dpp v205, v205, v205 row_half_mirror row_mask:0xf bank_mask:0xf bound_ctrl:1
	v_add_f32_dpp v206, v206, v206 row_half_mirror row_mask:0xf bank_mask:0xf bound_ctrl:1
	v_add_f32_dpp v207, v207, v207 row_half_mirror row_mask:0xf bank_mask:0xf bound_ctrl:1
	v_add_f32_dpp v204, v204, v204 row_mirror row_mask:0xf bank_mask:0xf bound_ctrl:1
	v_add_f32_dpp v205, v205, v205 row_mirror row_mask:0xf bank_mask:0xf bound_ctrl:1
	v_add_f32_dpp v206, v206, v206 row_mirror row_mask:0xf bank_mask:0xf bound_ctrl:1
	v_add_f32_dpp v207, v207, v207 row_mirror row_mask:0xf bank_mask:0xf bound_ctrl:1
	v_fmamk_f32 v204, v204, 0x3c800000, v231
	v_fmamk_f32 v205, v205, 0x3c800000, v231
	v_fmamk_f32 v206, v206, 0x3c800000, v231
	v_fmamk_f32 v207, v207, 0x3c800000, v231
	v_rsq_f32_e32 v204, v204
	v_rsq_f32_e32 v205, v205
	v_rsq_f32_e32 v206, v206
	v_rsq_f32_e32 v207, v207
	v_lshlrev_b32_e32 v208, 16, v122
	v_lshlrev_b32_e32 v209, 16, v124
	v_lshlrev_b32_e32 v210, 16, v126
	v_lshlrev_b32_e32 v211, 16, v128
	v_pk_mul_f32 v[212:213], v[212:213], v[204:205]
	v_pk_mul_f32 v[214:215], v[214:215], v[206:207]
	v_pk_mul_f32 v[212:213], v[212:213], v[208:209]
	v_pk_mul_f32 v[214:215], v[214:215], v[210:211]
	v_and_b32_e32 v208, 0xffff0000, v122
	v_and_b32_e32 v209, 0xffff0000, v124
	v_and_b32_e32 v210, 0xffff0000, v126
	v_and_b32_e32 v211, 0xffff0000, v128
	v_pk_mul_f32 v[216:217], v[216:217], v[204:205]
	v_pk_mul_f32 v[218:219], v[218:219], v[206:207]
	v_pk_mul_f32 v[216:217], v[216:217], v[208:209]
	v_pk_mul_f32 v[218:219], v[218:219], v[210:211]
	v_lshlrev_b32_e32 v208, 16, v123
	v_lshlrev_b32_e32 v209, 16, v125
	v_lshlrev_b32_e32 v210, 16, v127
	v_lshlrev_b32_e32 v211, 16, v129
	v_pk_mul_f32 v[224:225], v[224:225], v[204:205]
	v_pk_mul_f32 v[226:227], v[226:227], v[206:207]
	v_pk_mul_f32 v[224:225], v[224:225], v[208:209]
	v_pk_mul_f32 v[226:227], v[226:227], v[210:211]
	v_and_b32_e32 v208, 0xffff0000, v123
	v_and_b32_e32 v209, 0xffff0000, v125
	v_and_b32_e32 v210, 0xffff0000, v127
	v_and_b32_e32 v211, 0xffff0000, v129
	v_pk_mul_f32 v[242:243], v[242:243], v[204:205]
	v_pk_mul_f32 v[244:245], v[244:245], v[206:207]
	v_pk_mul_f32 v[242:243], v[242:243], v[208:209]
	v_pk_mul_f32 v[244:245], v[244:245], v[210:211]
	v_cvt_pk_bf16_f32 v204, v212, v216
	v_cvt_pk_bf16_f32 v205, v224, v242
	v_cvt_pk_bf16_f32 v210, v213, v217
	v_cvt_pk_bf16_f32 v211, v225, v243
	v_cvt_pk_bf16_f32 v206, v214, v218
	v_cvt_pk_bf16_f32 v207, v226, v244
	v_cvt_pk_bf16_f32 v218, v215, v219
	v_cvt_pk_bf16_f32 v219, v227, v245
	v_and_b32_e32 v220, 1, v232
	v_mul_u32_u24_e32 v220, 0x7f8, v220
	v_add_u32_e32 v220, v75, v220
	s_mov_b32 vcc_lo, 0x55555555
	s_mov_b32 vcc_hi, 0x55555555
	v_cndmask_b32_dpp v208, v210, v204, vcc quad_perm:[1,0,3,2] row_mask:0xf bank_mask:0xf
	v_cndmask_b32_dpp v209, v211, v205, vcc quad_perm:[1,0,3,2] row_mask:0xf bank_mask:0xf
	v_cndmask_b32_dpp v216, v218, v206, vcc quad_perm:[1,0,3,2] row_mask:0xf bank_mask:0xf
	v_cndmask_b32_dpp v217, v219, v207, vcc quad_perm:[1,0,3,2] row_mask:0xf bank_mask:0xf
	s_not_b64 vcc, vcc
	v_cndmask_b32_dpp v210, v204, v210, vcc quad_perm:[1,0,3,2] row_mask:0xf bank_mask:0xf
	v_cndmask_b32_dpp v211, v205, v211, vcc quad_perm:[1,0,3,2] row_mask:0xf bank_mask:0xf
	v_cndmask_b32_dpp v218, v206, v218, vcc quad_perm:[1,0,3,2] row_mask:0xf bank_mask:0xf
	v_cndmask_b32_dpp v219, v207, v219, vcc quad_perm:[1,0,3,2] row_mask:0xf bank_mask:0xf
	global_store_dwordx4 v220, v[208:211], s[6:7]
	s_add_u32 s6, s3, 0x1600
	s_addc_u32 s7, s5, 0
	global_store_dwordx4 v220, v[216:219], s[6:7]
	s_add_u32 s6, s3, 0x1e00
	s_addc_u32 s7, s5, 0
	s_cbranch_execz .LBB0_450

; template <int N> __device__ __forceinline__ float row16_bcast(float v) { return dppf<0x150 + N>(v); }
; __device__ __forceinline__ float frcp(float x) { return __builtin_amdgcn_rcpf(x); }
;     ...
;             S[t] = S[t] * gl + bv; O[t] = o * use.wi + ov; }
;     }
;     if (!GDN) {
; #pragma unroll
;         for (int i = 0; i < 4; ++i) { const float den = row16_bcast<0>(O[NT - 1][i]), fl = row16_bcast<1>(O[NT - 1][i]); const float dv = frcp(fmaxf(fabsf(den), fl));
; #pragma unroll
;             for (int t = 0; t < 4; ++t) O[t][i] *= dv; }
;     }
.LBB0_441:
	v_lshlrev_b32_e32 v168, 16, v97
	v_and_b32_e32 v169, 0xffff0000, v97
	v_pk_fma_f32 v[168:169], v[62:63], v[106:107], v[168:169]
	v_lshlrev_b32_e32 v106, 16, v98
	v_and_b32_e32 v107, 0xffff0000, v98
	v_lshlrev_b32_e32 v166, 16, v96
	v_and_b32_e32 v167, 0xffff0000, v96
	v_pk_fma_f32 v[106:107], v[60:61], v[108:109], v[106:107]
	v_lshlrev_b32_e32 v108, 16, v68
	v_and_b32_e32 v109, 0xffff0000, v68
	v_pk_fma_f32 v[104:105], v[60:61], v[104:105], v[166:167]
	v_lshlrev_b32_e32 v166, 16, v99
	v_and_b32_e32 v167, 0xffff0000, v99
	v_pk_fma_f32 v[108:109], v[60:61], v[112:113], v[108:109]
	v_lshlrev_b32_e32 v112, 16, v70
	v_and_b32_e32 v113, 0xffff0000, v70
	v_pk_fma_f32 v[110:111], v[62:63], v[110:111], v[166:167]
	v_lshlrev_b32_e32 v166, 16, v69
	v_and_b32_e32 v167, 0xffff0000, v69
	v_pk_fma_f32 v[116:117], v[60:61], v[116:117], v[112:113]
	v_mov_b32_e32 v112, v104
	v_mov_b32_e32 v113, v106
	v_pk_fma_f32 v[166:167], v[62:63], v[114:115], v[166:167]
	v_lshlrev_b32_e32 v114, 16, v71
	v_and_b32_e32 v115, 0xffff0000, v71
	v_max_f32_e64 v104, |v160|, v161
	v_pk_fma_f32 v[170:171], v[62:63], v[118:119], v[114:115]
	v_mov_b32_e32 v118, v108
	v_rcp_f32_e32 v108, v104
	v_max_f32_e64 v114, |v184|, v185
	v_rcp_f32_e32 v114, v114
	v_mov_b32_e32 v106, v105
	v_pk_mul_f32 v[104:105], v[106:107], v[108:109] op_sel_hi:[1,0]
	v_mov_b32_e32 v119, v116
	v_max_f32_e64 v106, |v158|, v159
	v_pk_mul_f32 v[112:113], v[112:113], v[114:115] op_sel_hi:[1,0]
	v_pk_mul_f32 v[114:115], v[118:119], v[114:115] op_sel_hi:[1,0]
	v_rcp_f32_e32 v118, v106
	v_mov_b32_e32 v116, v109
	v_pk_mul_f32 v[106:107], v[116:117], v[108:109] op_sel_hi:[1,0]
	v_mov_b32_e32 v108, v168
	v_mov_b32_e32 v109, v110
	v_pk_mul_f32 v[116:117], v[108:109], v[118:119] op_sel_hi:[1,0]
	v_max_f32_e64 v109, |v156|, v157
	v_rcp_f32_e32 v156, v109
	v_mov_b32_e32 v108, v166
	v_mov_b32_e32 v109, v170
	v_mov_b32_e32 v110, v169
	v_mov_b32_e32 v170, v167
	v_pk_mul_f32 v[118:119], v[108:109], v[118:119] op_sel_hi:[1,0]
	v_pk_mul_f32 v[110:111], v[110:111], v[156:157] op_sel_hi:[1,0]
	v_pk_mul_f32 v[108:109], v[170:171], v[156:157] op_sel_hi:[1,0]
	s_cmp_lt_u32 s0, 16
	s_mov_b64 s[10:11], -1
	s_waitcnt lgkmcnt(0)
	s_barrier
	s_cbranch_scc1 .LBB0_453
; __device__ __forceinline__ float row16_sum(float v) { v += dppf<0xB1>(v); v += dppf<0x4E>(v); v += dppf<0x141>(v); v += dppf<0x140>(v); return v; }
; __device__ __forceinline__ float frsq(float x) { return __builtin_amdgcn_rsqf(x); }
; __device__ __forceinline__ v2u pack4(const f32x4 v) { v2u r; r.x = pk2(v[0], v[1]); r.y = pk2(v[2], v[3]); return r; }
; __device__ __forceinline__ f32x4 unpack4(const v2u w) { f32x4 r; r[0] = bflo(w.x); r[1] = bfhi(w.x); r[2] = bflo(w.y); r[3] = bfhi(w.y); return r; }
; __device__ __forceinline__ const char* upin(const char* p) { asm volatile("" : "+s"(p)); return p; }
; __device__ __forceinline__ char* upin(char* p) { asm volatile("" : "+s"(p)); return p; }
; template <bool GDN> __device__ __forceinline__ void scan_finish(const Frame& F, int b, int h, int dir, const ScanLane& L, int s, float* PEND, const f32x4 (&Oin)[4], const ScanFin& f) {
;     ...
;         f32x4 O[4]; float ss[4] = {0.f, 0.f, 0.f, 0.f};
; #pragma unroll
;         for (int t = 0; t < 4; ++t)
;             { const f32x4 pv = unpack4(f.pend[t]);
; #pragma unroll
;             for (int i = 0; i < 4; ++i) { O[t][i] = Oin[t][i] + pv[i]; ss[i] += O[t][i] * O[t][i]; } }
; #pragma unroll
;         for (int i = 0; i < 4; ++i) ss[i] = frsq(row16_sum(ss[i]) * (1.f / 64.f) + EPS);
;         char* mp = (char*)F.MIX + ((size_t)row0 * 1024 + (GDN ? 0 : 768) + h * 64) * 2;
; #pragma unroll
;         for (int i = 0; i < 4; ++i) { const f32x4 g = unpack4(f.gz[i]); f32x4 ov;
; #pragma unroll
;             for (int t = 0; t < 4; ++t) ov[t] = O[t][i] * ss[i] * g[t];
;             stu<v2u>(upin(mp + i * 2048), L.mix, pack4(ov)); }
	s_lshl_b32 s0, s1, 6
	s_cmp_lt_i32 s1, 4
	s_cselect_b32 s4, s63, s33
	s_add_i32 s4, s4, s0
	s_ashr_i32 s5, s4, 31
	s_lshl_b64 s[4:5], s[4:5], 11
	s_add_u32 s0, s26, s4
	s_addc_u32 s6, s27, s5
	s_add_u32 s4, s0, 0x600
	s_addc_u32 s5, s6, 0
	v_lshlrev_b32_e32 v246, 16, v12
	v_lshlrev_b32_e32 v247, 16, v14
	v_lshlrev_b32_e32 v220, 16, v16
	v_lshlrev_b32_e32 v221, 16, v18
	v_pk_add_f32 v[212:213], v[112:113], v[246:247]
	v_pk_add_f32 v[214:215], v[114:115], v[220:221]
	v_pk_mul_f32 v[204:205], v[212:213], v[212:213]
	v_pk_fma_f32 v[204:205], v[214:215], v[214:215], v[204:205]
	v_and_b32_e32 v246, 0xffff0000, v12
	v_and_b32_e32 v247, 0xffff0000, v14
	v_and_b32_e32 v220, 0xffff0000, v16
	v_and_b32_e32 v221, 0xffff0000, v18
	v_pk_add_f32 v[216:217], v[104:105], v[246:247]
	v_pk_add_f32 v[218:219], v[106:107], v[220:221]
	v_pk_mul_f32 v[206:207], v[216:217], v[216:217]
	v_pk_fma_f32 v[206:207], v[218:219], v[218:219], v[206:207]
	v_lshlrev_b32_e32 v246, 16, v13
	v_lshlrev_b32_e32 v247, 16, v15
	v_lshlrev_b32_e32 v220, 16, v17
	v_lshlrev_b32_e32 v221, 16, v19
	v_pk_add_f32 v[224:225], v[116:117], v[246:247]
	v_pk_add_f32 v[226:227], v[118:119], v[220:221]
	v_pk_mul_f32 v[208:209], v[224:225], v[224:225]
	v_pk_fma_f32 v[208:209], v[226:227], v[226:227], v[208:209]
	v_and_b32_e32 v246, 0xffff0000, v13
	v_and_b32_e32 v247, 0xffff0000, v15
	v_and_b32_e32 v220, 0xffff0000, v17
	v_and_b32_e32 v221, 0xffff0000, v19
	v_pk_add_f32 v[242:243], v[110:111], v[246:247]
	v_pk_add_f32 v[244:245], v[108:109], v[220:221]
	v_pk_mul_f32 v[210:211], v[242:243], v[242:243]
	v_pk_fma_f32 v[210:211], v[244:245], v[244:245], v[210:211]
	v_add_f32_e32 v204, v204, v205
	v_add_f32_e32 v206, v206, v207
	v_add_f32_e32 v208, v208, v209
	v_add_f32_e32 v210, v210, v211
	s_nop 0
	v_add_f32_dpp v204, v204, v204 quad_perm:[1,0,3,2] row_mask:0xf bank_mask:0xf bound_ctrl:1
	v_add_f32_dpp v206, v206, v206 quad_perm:[1,0,3,2] row_mask:0xf bank_mask:0xf bound_ctrl:1
	v_add_f32_dpp v208, v208, v208 quad_perm:[1,0,3,2] row_mask:0xf bank_mask:0xf bound_ctrl:1
	v_add_f32_dpp v210, v210, v210 quad_perm:[1,0,3,2] row_mask:0xf bank_mask:0xf bound_ctrl:1
	v_add_f32_dpp v204, v204, v204 quad_perm:[2,3,0,1] row_mask:0xf bank_mask:0xf bound_ctrl:1
	v_add_f32_dpp v206, v206, v206 quad_perm:[2,3,0,1] row_mask:0xf bank_mask:0xf bound_ctrl:1
	v_add_f32_dpp v208, v208, v208 quad_perm:[2,3,0,1] row_mask:0xf bank_mask:0xf bound_ctrl:1
	v_add_f32_dpp v210, v210, v210 quad_perm:[2,3,0,1] row_mask:0xf bank_mask:0xf bound_ctrl:1
	v_add_f32_dpp v204, v204, v204 row_half_mirror row_mask:0xf bank_mask:0xf bound_ctrl:1
	v_add_f32_dpp v206, v206, v206 row_half_mirror row_mask:0xf bank_mask:0xf bound_ctrl:1
	v_add_f32_dpp v208, v208, v208 row_half_mirror row_mask:0xf bank_mask:0xf bound_ctrl:1
	v_add_f32_dpp v210, v210, v210 row_half_mirror row_mask:0xf bank_mask:0xf bound_ctrl:1
	v_add_f32_dpp v204, v204, v204 row_mirror row_mask:0xf bank_mask:0xf bound_ctrl:1
	v_add_f32_dpp v206, v206, v206 row_mirror row_mask:0xf bank_mask:0xf bound_ctrl:1
	v_add_f32_dpp v208, v208, v208 row_mirror row_mask:0xf bank_mask:0xf bound_ctrl:1
	v_add_f32_dpp v210, v210, v210 row_mirror row_mask:0xf bank_mask:0xf bound_ctrl:1
	v_fmamk_f32 v204, v204, 0x3c800000, v231
	v_fmamk_f32 v206, v206, 0x3c800000, v231
	v_fmamk_f32 v208, v208, 0x3c800000, v231
	v_fmamk_f32 v210, v210, 0x3c800000, v231
	v_rsq_f32_e32 v204, v204
	v_rsq_f32_e32 v206, v206
	v_rsq_f32_e32 v208, v208
	v_rsq_f32_e32 v210, v210
	v_lshlrev_b32_e32 v246, 16, v130
	v_and_b32_e32 v247, 0xffff0000, v130
	v_lshlrev_b32_e32 v220, 16, v131
	v_and_b32_e32 v221, 0xffff0000, v131
	v_pk_mul_f32 v[212:213], v[212:213], v[204:205] op_sel_hi:[1,0]
	v_pk_mul_f32 v[214:215], v[214:215], v[204:205] op_sel_hi:[1,0]
	v_pk_mul_f32 v[212:213], v[212:213], v[246:247]
	v_pk_mul_f32 v[214:215], v[214:215], v[220:221]
	v_lshlrev_b32_e32 v246, 16, v132
	v_and_b32_e32 v247, 0xffff0000, v132
	v_lshlrev_b32_e32 v220, 16, v133
	v_and_b32_e32 v221, 0xffff0000, v133
	v_pk_mul_f32 v[216:217], v[216:217], v[206:207] op_sel_hi:[1,0]
	v_pk_mul_f32 v[218:219], v[218:219], v[206:207] op_sel_hi:[1,0]
	v_pk_mul_f32 v[216:217], v[216:217], v[246:247]
	v_pk_mul_f32 v[218:219], v[218:219], v[220:221]
	v_lshlrev_b32_e32 v246, 16, v134
	v_and_b32_e32 v247, 0xffff0000, v134
	v_lshlrev_b32_e32 v220, 16, v135
	v_and_b32_e32 v221, 0xffff0000, v135
	v_pk_mul_f32 v[224:225], v[224:225], v[208:209] op_sel_hi:[1,0]
	v_pk_mul_f32 v[226:227], v[226:227], v[208:209] op_sel_hi:[1,0]
	v_pk_mul_f32 v[224:225], v[224:225], v[246:247]
	v_pk_mul_f32 v[226:227], v[226:227], v[220:221]
	v_lshlrev_b32_e32 v246, 16, v136
	v_and_b32_e32 v247, 0xffff0000, v136
	v_lshlrev_b32_e32 v220, 16, v137
	v_and_b32_e32 v221, 0xffff0000, v137
	v_pk_mul_f32 v[242:243], v[242:243], v[210:211] op_sel_hi:[1,0]
	v_pk_mul_f32 v[244:245], v[244:245], v[210:211] op_sel_hi:[1,0]
	v_pk_mul_f32 v[242:243], v[242:243], v[246:247]
	v_pk_mul_f32 v[244:245], v[244:245], v[220:221]
	v_cvt_pk_bf16_f32 v204, v212, v213
	v_cvt_pk_bf16_f32 v205, v214, v215
	v_cvt_pk_bf16_f32 v210, v216, v217
	v_cvt_pk_bf16_f32 v211, v218, v219
	v_cvt_pk_bf16_f32 v206, v224, v225
	v_cvt_pk_bf16_f32 v207, v226, v227
	v_cvt_pk_bf16_f32 v218, v242, v243
	v_cvt_pk_bf16_f32 v219, v244, v245
	v_and_b32_e32 v220, 1, v232
	v_mul_u32_u24_e32 v220, 0x7f8, v220
	v_add_u32_e32 v220, v153, v220
	s_mov_b32 vcc_lo, 0x55555555
	s_mov_b32 vcc_hi, 0x55555555
	v_cndmask_b32_dpp v208, v210, v204, vcc quad_perm:[1,0,3,2] row_mask:0xf bank_mask:0xf
	v_cndmask_b32_dpp v209, v211, v205, vcc quad_perm:[1,0,3,2] row_mask:0xf bank_mask:0xf
	v_cndmask_b32_dpp v216, v218, v206, vcc quad_perm:[1,0,3,2] row_mask:0xf bank_mask:0xf
	v_cndmask_b32_dpp v217, v219, v207, vcc quad_perm:[1,0,3,2] row_mask:0xf bank_mask:0xf
	s_not_b64 vcc, vcc
	v_cndmask_b32_dpp v210, v204, v210, vcc quad_perm:[1,0,3,2] row_mask:0xf bank_mask:0xf
	v_cndmask_b32_dpp v211, v205, v211, vcc quad_perm:[1,0,3,2] row_mask:0xf bank_mask:0xf
	v_cndmask_b32_dpp v218, v206, v218, vcc quad_perm:[1,0,3,2] row_mask:0xf bank_mask:0xf
	v_cndmask_b32_dpp v219, v207, v219, vcc quad_perm:[1,0,3,2] row_mask:0xf bank_mask:0xf
	global_store_dwordx4 v220, v[208:211], s[4:5]
	s_add_u32 s4, s0, 0x1600
	s_addc_u32 s5, s6, 0
	global_store_dwordx4 v220, v[216:219], s[4:5]
	s_add_u32 s4, s0, 0x1e00
	s_addc_u32 s5, s6, 0
	s_cbranch_execz .LBB0_454

; __device__ __forceinline__ float row16_sum(float v) { v += dppf<0xB1>(v); v += dppf<0x4E>(v); v += dppf<0x141>(v); v += dppf<0x140>(v); return v; }
; __device__ __forceinline__ float frsq(float x) { return __builtin_amdgcn_rsqf(x); }
; __device__ __forceinline__ v2u pack4(const f32x4 v) { v2u r; r.x = pk2(v[0], v[1]); r.y = pk2(v[2], v[3]); return r; }
; __device__ __forceinline__ f32x4 unpack4(const v2u w) { f32x4 r; r[0] = bflo(w.x); r[1] = bfhi(w.x); r[2] = bflo(w.y); r[3] = bfhi(w.y); return r; }
; __device__ __forceinline__ const char* upin(const char* p) { asm volatile("" : "+s"(p)); return p; }
; __device__ __forceinline__ char* upin(char* p) { asm volatile("" : "+s"(p)); return p; }
; template <bool GDN> __device__ __forceinline__ void scan_finish(const Frame& F, int b, int h, int dir, const ScanLane& L, int s, float* PEND, const f32x4 (&Oin)[4], const ScanFin& f) {
;     const int cidx = dir ? (s < 4 ? 3 - s : 39 - s) : s; const int row0 = chunk_row0(b, cidx);
;     if (scan_first(s)) {
;         char* pp = upin((char*)PEND + (size_t)((b * 4 + h) * 36 + cidx) * 16384);
; #pragma unroll
;         for (int pr = 0; pr < 2; ++pr) { const v2u a = pack4(Oin[2 * pr]), bq = pack4(Oin[2 * pr + 1]); v4u o; o.x = a.x; o.y = a.y; o.z = bq.x; o.w = bq.y; stu<v4u>(pp + pr * 1024, L.pend, o); }
;     } else {
;         f32x4 O[4]; float ss[4] = {0.f, 0.f, 0.f, 0.f};
; #pragma unroll
;         for (int t = 0; t < 4; ++t)
;             { const f32x4 pv = unpack4(f.pend[t]);
; #pragma unroll
;             for (int i = 0; i < 4; ++i) { O[t][i] = Oin[t][i] + pv[i]; ss[i] += O[t][i] * O[t][i]; } }
; #pragma unroll
;         for (int i = 0; i < 4; ++i) ss[i] = frsq(row16_sum(ss[i]) * (1.f / 64.f) + EPS);
;         char* mp = (char*)F.MIX + ((size_t)row0 * 1024 + (GDN ? 0 : 768) + h * 64) * 2;
; #pragma unroll
;         for (int i = 0; i < 4; ++i) { const f32x4 g = unpack4(f.gz[i]); f32x4 ov;
; #pragma unroll
;             for (int t = 0; t < 4; ++t) ov[t] = O[t][i] * ss[i] * g[t];
;             stu<v2u>(upin(mp + i * 2048), L.mix, pack4(ov)); }
.LBB0_469:
	s_lshl_b32 s1, s0, 6
	s_cmp_lt_i32 s0, 4
	s_cselect_b32 s3, s63, s33
	s_add_i32 s4, s3, s1
	s_ashr_i32 s5, s4, 31
	s_lshl_b64 s[4:5], s[4:5], 11
	s_add_u32 s1, s26, s4
	s_addc_u32 s3, s27, s5
	s_add_u32 s4, s1, 0x600
	s_addc_u32 s5, s3, 0
	v_lshlrev_b32_e32 v208, 16, v4
	v_and_b32_e32 v209, 0xffff0000, v4
	v_lshlrev_b32_e32 v210, 16, v5
	v_and_b32_e32 v211, 0xffff0000, v5
	v_pk_add_f32 v[212:213], v[24:25], v[208:209]
	v_pk_add_f32 v[214:215], v[20:21], v[210:211]
	v_pk_mul_f32 v[204:205], v[212:213], v[212:213]
	v_pk_mul_f32 v[206:207], v[214:215], v[214:215]
	v_lshlrev_b32_e32 v208, 16, v6
	v_and_b32_e32 v209, 0xffff0000, v6
	v_lshlrev_b32_e32 v210, 16, v7
	v_and_b32_e32 v211, 0xffff0000, v7
	v_pk_add_f32 v[216:217], v[104:105], v[208:209]
	v_pk_add_f32 v[218:219], v[110:111], v[210:211]
	v_pk_fma_f32 v[204:205], v[216:217], v[216:217], v[204:205]
	v_pk_fma_f32 v[206:207], v[218:219], v[218:219], v[206:207]
	v_lshlrev_b32_e32 v208, 16, v8
	v_and_b32_e32 v209, 0xffff0000, v8
	v_lshlrev_b32_e32 v210, 16, v9
	v_and_b32_e32 v211, 0xffff0000, v9
	v_pk_add_f32 v[224:225], v[26:27], v[208:209]
	v_pk_add_f32 v[226:227], v[22:23], v[210:211]
	v_pk_fma_f32 v[204:205], v[224:225], v[224:225], v[204:205]
	v_pk_fma_f32 v[206:207], v[226:227], v[226:227], v[206:207]
	v_lshlrev_b32_e32 v208, 16, v10
	v_and_b32_e32 v209, 0xffff0000, v10
	v_lshlrev_b32_e32 v210, 16, v11
	v_and_b32_e32 v211, 0xffff0000, v11
	v_pk_add_f32 v[242:243], v[106:107], v[208:209]
	v_pk_add_f32 v[244:245], v[108:109], v[210:211]
	v_pk_fma_f32 v[204:205], v[242:243], v[242:243], v[204:205]
	v_pk_fma_f32 v[206:207], v[244:245], v[244:245], v[206:207]
	s_nop 1
	v_add_f32_dpp v204, v204, v204 quad_perm:[1,0,3,2] row_mask:0xf bank_mask:0xf bound_ctrl:1
	v_add_f32_dpp v205, v205, v205 quad_perm:[1,0,3,2] row_mask:0xf bank_mask:0xf bound_ctrl:1
	v_add_f32_dpp v206, v206, v206 quad_perm:[1,0,3,2] row_mask:0xf bank_mask:0xf bound_ctrl:1
	v_add_f32_dpp v207, v207, v207 quad_perm:[1,0,3,2] row_mask:0xf bank_mask:0xf bound_ctrl:1
	v_add_f32_dpp v204, v204, v204 quad_perm:[2,3,0,1] row_mask:0xf bank_mask:0xf bound_ctrl:1
	v_add_f32_dpp v205, v205, v205 quad_perm:[2,3,0,1] row_mask:0xf bank_mask:0xf bound_ctrl:1
	v_add_f32_dpp v206, v206, v206 quad_perm:[2,3,0,1] row_mask:0xf bank_mask:0xf bound_ctrl:1
	v_add_f32_dpp v207, v207, v207 quad_perm:[2,3,0,1] row_mask:0xf bank_mask:0xf bound_ctrl:1
	v_add_f32_dpp v204, v204, v204 row_half_mirror row_mask:0xf bank_mask:0xf bound_ctrl:1
	v_add_f32_dpp v205, v205, v205 row_half_mirror row_mask:0xf bank_mask:0xf bound_ctrl:1
	v_add_f32_dpp v206, v206, v206 row_half_mirror row_mask:0xf bank_mask:0xf bound_ctrl:1
	v_add_f32_dpp v207, v207, v207 row_half_mirror row_mask:0xf bank_mask:0xf bound_ctrl:1
	v_add_f32_dpp v204, v204, v204 row_mirror row_mask:0xf bank_mask:0xf bound_ctrl:1
	v_add_f32_dpp v205, v205, v205 row_mirror row_mask:0xf bank_mask:0xf bound_ctrl:1
	v_add_f32_dpp v206, v206, v206 row_mirror row_mask:0xf bank_mask:0xf bound_ctrl:1
	v_add_f32_dpp v207, v207, v207 row_mirror row_mask:0xf bank_mask:0xf bound_ctrl:1
	v_fmamk_f32 v204, v204, 0x3c800000, v231
	v_fmamk_f32 v205, v205, 0x3c800000, v231
	v_fmamk_f32 v206, v206, 0x3c800000, v231
	v_fmamk_f32 v207, v207, 0x3c800000, v231
	v_rsq_f32_e32 v204, v204
	v_rsq_f32_e32 v205, v205
	v_rsq_f32_e32 v206, v206
	v_rsq_f32_e32 v207, v207
	v_lshlrev_b32_e32 v208, 16, v122
	v_lshlrev_b32_e32 v209, 16, v124
	v_lshlrev_b32_e32 v210, 16, v126
	v_lshlrev_b32_e32 v211, 16, v128
	v_pk_mul_f32 v[212:213], v[212:213], v[204:205]
	v_pk_mul_f32 v[214:215], v[214:215], v[206:207]
	v_pk_mul_f32 v[212:213], v[212:213], v[208:209]
	v_pk_mul_f32 v[214:215], v[214:215], v[210:211]
	v_and_b32_e32 v208, 0xffff0000, v122
	v_and_b32_e32 v209, 0xffff0000, v124
	v_and_b32_e32 v210, 0xffff0000, v126
	v_and_b32_e32 v211, 0xffff0000, v128
	v_pk_mul_f32 v[216:217], v[216:217], v[204:205]
	v_pk_mul_f32 v[218:219], v[218:219], v[206:207]
	v_pk_mul_f32 v[216:217], v[216:217], v[208:209]
	v_pk_mul_f32 v[218:219], v[218:219], v[210:211]
	v_lshlrev_b32_e32 v208, 16, v123
	v_lshlrev_b32_e32 v209, 16, v125
	v_lshlrev_b32_e32 v210, 16, v127
	v_lshlrev_b32_e32 v211, 16, v129
	v_pk_mul_f32 v[224:225], v[224:225], v[204:205]
	v_pk_mul_f32 v[226:227], v[226:227], v[206:207]
	v_pk_mul_f32 v[224:225], v[224:225], v[208:209]
	v_pk_mul_f32 v[226:227], v[226:227], v[210:211]
	v_and_b32_e32 v208, 0xffff0000, v123
	v_and_b32_e32 v209, 0xffff0000, v125
	v_and_b32_e32 v210, 0xffff0000, v127
	v_and_b32_e32 v211, 0xffff0000, v129
	v_pk_mul_f32 v[242:243], v[242:243], v[204:205]
	v_pk_mul_f32 v[244:245], v[244:245], v[206:207]
	v_pk_mul_f32 v[242:243], v[242:243], v[208:209]
	v_pk_mul_f32 v[244:245], v[244:245], v[210:211]
	v_cvt_pk_bf16_f32 v204, v212, v216
	v_cvt_pk_bf16_f32 v205, v224, v242
	v_cvt_pk_bf16_f32 v210, v213, v217
	v_cvt_pk_bf16_f32 v211, v225, v243
	v_cvt_pk_bf16_f32 v206, v214, v218
	v_cvt_pk_bf16_f32 v207, v226, v244
	v_cvt_pk_bf16_f32 v218, v215, v219
	v_cvt_pk_bf16_f32 v219, v227, v245
	v_and_b32_e32 v220, 1, v232
	v_mul_u32_u24_e32 v220, 0x7f8, v220
	v_add_u32_e32 v220, v31, v220
	s_mov_b32 vcc_lo, 0x55555555
	s_mov_b32 vcc_hi, 0x55555555
	v_cndmask_b32_dpp v208, v210, v204, vcc quad_perm:[1,0,3,2] row_mask:0xf bank_mask:0xf
	v_cndmask_b32_dpp v209, v211, v205, vcc quad_perm:[1,0,3,2] row_mask:0xf bank_mask:0xf
	v_cndmask_b32_dpp v216, v218, v206, vcc quad_perm:[1,0,3,2] row_mask:0xf bank_mask:0xf
	v_cndmask_b32_dpp v217, v219, v207, vcc quad_perm:[1,0,3,2] row_mask:0xf bank_mask:0xf
	s_not_b64 vcc, vcc
	v_cndmask_b32_dpp v210, v204, v210, vcc quad_perm:[1,0,3,2] row_mask:0xf bank_mask:0xf
	v_cndmask_b32_dpp v211, v205, v211, vcc quad_perm:[1,0,3,2] row_mask:0xf bank_mask:0xf
	v_cndmask_b32_dpp v218, v206, v218, vcc quad_perm:[1,0,3,2] row_mask:0xf bank_mask:0xf
	v_cndmask_b32_dpp v219, v207, v219, vcc quad_perm:[1,0,3,2] row_mask:0xf bank_mask:0xf
	global_store_dwordx4 v220, v[208:211], s[4:5]
	s_add_u32 s4, s1, 0x1600
	s_addc_u32 s5, s3, 0
	global_store_dwordx4 v220, v[216:219], s[4:5]
	s_add_u32 s4, s1, 0x1e00
	s_addc_u32 s5, s3, 0
	s_cbranch_execz .LBB0_474

; __device__ __forceinline__ float row16_sum(float v) { v += dppf<0xB1>(v); v += dppf<0x4E>(v); v += dppf<0x141>(v); v += dppf<0x140>(v); return v; }
; __device__ __forceinline__ float frsq(float x) { return __builtin_amdgcn_rsqf(x); }
; __device__ __forceinline__ v2u pack4(const f32x4 v) { v2u r; r.x = pk2(v[0], v[1]); r.y = pk2(v[2], v[3]); return r; }
; __device__ __forceinline__ f32x4 unpack4(const v2u w) { f32x4 r; r[0] = bflo(w.x); r[1] = bfhi(w.x); r[2] = bflo(w.y); r[3] = bfhi(w.y); return r; }
; __device__ __forceinline__ const char* upin(const char* p) { asm volatile("" : "+s"(p)); return p; }
; __device__ __forceinline__ char* upin(char* p) { asm volatile("" : "+s"(p)); return p; }
; template <bool GDN> __device__ __forceinline__ void scan_finish(const Frame& F, int b, int h, int dir, const ScanLane& L, int s, float* PEND, const f32x4 (&Oin)[4], const ScanFin& f) {
;     const int cidx = dir ? (s < 4 ? 3 - s : 39 - s) : s; const int row0 = chunk_row0(b, cidx);
;     if (scan_first(s)) {
;         char* pp = upin((char*)PEND + (size_t)((b * 4 + h) * 36 + cidx) * 16384);
; #pragma unroll
;         for (int pr = 0; pr < 2; ++pr) { const v2u a = pack4(Oin[2 * pr]), bq = pack4(Oin[2 * pr + 1]); v4u o; o.x = a.x; o.y = a.y; o.z = bq.x; o.w = bq.y; stu<v4u>(pp + pr * 1024, L.pend, o); }
;     } else {
;         f32x4 O[4]; float ss[4] = {0.f, 0.f, 0.f, 0.f};
; #pragma unroll
;         for (int t = 0; t < 4; ++t)
;             { const f32x4 pv = unpack4(f.pend[t]);
; #pragma unroll
;             for (int i = 0; i < 4; ++i) { O[t][i] = Oin[t][i] + pv[i]; ss[i] += O[t][i] * O[t][i]; } }
; #pragma unroll
;         for (int i = 0; i < 4; ++i) ss[i] = frsq(row16_sum(ss[i]) * (1.f / 64.f) + EPS);
;         char* mp = (char*)F.MIX + ((size_t)row0 * 1024 + (GDN ? 0 : 768) + h * 64) * 2;
; #pragma unroll
;         for (int i = 0; i < 4; ++i) { const f32x4 g = unpack4(f.gz[i]); f32x4 ov;
; #pragma unroll
;             for (int t = 0; t < 4; ++t) ov[t] = O[t][i] * ss[i] * g[t];
;             stu<v2u>(upin(mp + i * 2048), L.mix, pack4(ov)); }
;     ...
;     __syncthreads();
;     if (s > 0) {
;         const int sp = s - 1;
;         if (sp == 20 || sp == 2) { asm volatile("s_waitcnt vmcnt(0)" ::: "memory"); scan_fin_load<GDN>(F, b, h, dir, L, sp, PEND, fin); }
;         if (!nofin) scan_finish<GDN>(F, b, h, dir, L, sp, PEND, Oprev, fin);
.LBB0_487:
	s_add_i32 s0, s23, -1
	s_cmp_eq_u32 s23, 0
	s_cselect_b64 s[10:11], -1, 0
	s_and_b64 vcc, exec, s[10:11]
	s_waitcnt lgkmcnt(0)
	s_barrier
	s_cbranch_vccnz .LBB0_492
	s_add_i32 s1, s22, 43
	s_and_b64 s[4:5], s[90:91], exec
	s_cselect_b32 s1, s0, s1
	s_cmp_lt_u32 s23, 5
	s_cselect_b32 s3, 2, 20
	s_cmp_lt_u32 s0, s3
	s_mov_b64 s[12:13], -1
	s_cbranch_scc1 .LBB0_490
	s_cmp_lt_i32 s1, 4
	s_cselect_b32 s3, s25, s24
	s_lshl_b32 s4, s1, 6
	s_add_i32 s4, s3, s4
	s_ashr_i32 s5, s4, 31
	s_lshl_b64 s[4:5], s[4:5], 11
	s_add_u32 s18, s26, s4
	s_addc_u32 s19, s27, s5
	s_mov_b64 s[4:5], s[18:19]
	v_lshlrev_b32_e32 v208, 16, v10
	v_and_b32_e32 v209, 0xffff0000, v10
	v_lshlrev_b32_e32 v210, 16, v11
	v_and_b32_e32 v211, 0xffff0000, v11
	v_pk_add_f32 v[212:213], v[130:131], v[208:209]
	v_pk_add_f32 v[214:215], v[132:133], v[210:211]
	v_pk_mul_f32 v[204:205], v[212:213], v[212:213]
	v_pk_mul_f32 v[206:207], v[214:215], v[214:215]
	v_lshlrev_b32_e32 v208, 16, v12
	v_and_b32_e32 v209, 0xffff0000, v12
	v_lshlrev_b32_e32 v210, 16, v13
	v_and_b32_e32 v211, 0xffff0000, v13
	v_pk_add_f32 v[216:217], v[134:135], v[208:209]
	v_pk_add_f32 v[218:219], v[136:137], v[210:211]
	v_pk_fma_f32 v[204:205], v[216:217], v[216:217], v[204:205]
	v_pk_fma_f32 v[206:207], v[218:219], v[218:219], v[206:207]
	v_lshlrev_b32_e32 v208, 16, v14
	v_and_b32_e32 v209, 0xffff0000, v14
	v_lshlrev_b32_e32 v210, 16, v15
	v_and_b32_e32 v211, 0xffff0000, v15
	v_pk_add_f32 v[224:225], v[138:139], v[208:209]
	v_pk_add_f32 v[226:227], v[140:141], v[210:211]
	v_pk_fma_f32 v[204:205], v[224:225], v[224:225], v[204:205]
	v_pk_fma_f32 v[206:207], v[226:227], v[226:227], v[206:207]
	v_lshlrev_b32_e32 v208, 16, v16
	v_and_b32_e32 v209, 0xffff0000, v16
	v_lshlrev_b32_e32 v210, 16, v17
	v_and_b32_e32 v211, 0xffff0000, v17
	v_pk_add_f32 v[242:243], v[142:143], v[208:209]
	v_pk_add_f32 v[244:245], v[144:145], v[210:211]
	v_pk_fma_f32 v[204:205], v[242:243], v[242:243], v[204:205]
	v_pk_fma_f32 v[206:207], v[244:245], v[244:245], v[206:207]
	s_nop 1
	v_add_f32_dpp v204, v204, v204 quad_perm:[1,0,3,2] row_mask:0xf bank_mask:0xf bound_ctrl:1
	v_add_f32_dpp v205, v205, v205 quad_perm:[1,0,3,2] row_mask:0xf bank_mask:0xf bound_ctrl:1
	v_add_f32_dpp v206, v206, v206 quad_perm:[1,0,3,2] row_mask:0xf bank_mask:0xf bound_ctrl:1
	v_add_f32_dpp v207, v207, v207 quad_perm:[1,0,3,2] row_mask:0xf bank_mask:0xf bound_ctrl:1
	v_add_f32_dpp v204, v204, v204 quad_perm:[2,3,0,1] row_mask:0xf bank_mask:0xf bound_ctrl:1
	v_add_f32_dpp v205, v205, v205 quad_perm:[2,3,0,1] row_mask:0xf bank_mask:0xf bound_ctrl:1
	v_add_f32_dpp v206, v206, v206 quad_perm:[2,3,0,1] row_mask:0xf bank_mask:0xf bound_ctrl:1
	v_add_f32_dpp v207, v207, v207 quad_perm:[2,3,0,1] row_mask:0xf bank_mask:0xf bound_ctrl:1
	v_add_f32_dpp v204, v204, v204 row_half_mirror row_mask:0xf bank_mask:0xf bound_ctrl:1
	v_add_f32_dpp v205, v205, v205 row_half_mirror row_mask:0xf bank_mask:0xf bound_ctrl:1
	v_add_f32_dpp v206, v206, v206 row_half_mirror row_mask:0xf bank_mask:0xf bound_ctrl:1
	v_add_f32_dpp v207, v207, v207 row_half_mirror row_mask:0xf bank_mask:0xf bound_ctrl:1
	v_add_f32_dpp v204, v204, v204 row_mirror row_mask:0xf bank_mask:0xf bound_ctrl:1
	v_add_f32_dpp v205, v205, v205 row_mirror row_mask:0xf bank_mask:0xf bound_ctrl:1
	v_add_f32_dpp v206, v206, v206 row_mirror row_mask:0xf bank_mask:0xf bound_ctrl:1
	v_add_f32_dpp v207, v207, v207 row_mirror row_mask:0xf bank_mask:0xf bound_ctrl:1
	v_fmamk_f32 v204, v204, 0x3c800000, v231
	v_fmamk_f32 v205, v205, 0x3c800000, v231
	v_fmamk_f32 v206, v206, 0x3c800000, v231
	v_fmamk_f32 v207, v207, 0x3c800000, v231
	v_rsq_f32_e32 v204, v204
	v_rsq_f32_e32 v205, v205
	v_rsq_f32_e32 v206, v206
	v_rsq_f32_e32 v207, v207
	v_lshlrev_b32_e32 v208, 16, v164
	v_lshlrev_b32_e32 v209, 16, v178
	v_lshlrev_b32_e32 v210, 16, v180
	v_lshlrev_b32_e32 v211, 16, v182
	v_pk_mul_f32 v[212:213], v[212:213], v[204:205]
	v_pk_mul_f32 v[214:215], v[214:215], v[206:207]
	v_pk_mul_f32 v[212:213], v[212:213], v[208:209]
	v_pk_mul_f32 v[214:215], v[214:215], v[210:211]
	v_and_b32_e32 v208, 0xffff0000, v164
	v_and_b32_e32 v209, 0xffff0000, v178
	v_and_b32_e32 v210, 0xffff0000, v180
	v_and_b32_e32 v211, 0xffff0000, v182
	v_pk_mul_f32 v[216:217], v[216:217], v[204:205]
	v_pk_mul_f32 v[218:219], v[218:219], v[206:207]
	v_pk_mul_f32 v[216:217], v[216:217], v[208:209]
	v_pk_mul_f32 v[218:219], v[218:219], v[210:211]
	v_lshlrev_b32_e32 v208, 16, v165
	v_lshlrev_b32_e32 v209, 16, v179
	v_lshlrev_b32_e32 v210, 16, v181
	v_lshlrev_b32_e32 v211, 16, v183
	v_pk_mul_f32 v[224:225], v[224:225], v[204:205]
	v_pk_mul_f32 v[226:227], v[226:227], v[206:207]
	v_pk_mul_f32 v[224:225], v[224:225], v[208:209]
	v_pk_mul_f32 v[226:227], v[226:227], v[210:211]
	v_and_b32_e32 v208, 0xffff0000, v165
	v_and_b32_e32 v209, 0xffff0000, v179
	v_and_b32_e32 v210, 0xffff0000, v181
	v_and_b32_e32 v211, 0xffff0000, v183
	v_pk_mul_f32 v[242:243], v[242:243], v[204:205]
	v_pk_mul_f32 v[244:245], v[244:245], v[206:207]
	v_pk_mul_f32 v[242:243], v[242:243], v[208:209]
	v_pk_mul_f32 v[244:245], v[244:245], v[210:211]
	v_cvt_pk_bf16_f32 v204, v212, v216
	v_cvt_pk_bf16_f32 v205, v224, v242
	v_cvt_pk_bf16_f32 v210, v213, v217
	v_cvt_pk_bf16_f32 v211, v225, v243
	v_cvt_pk_bf16_f32 v206, v214, v218
	v_cvt_pk_bf16_f32 v207, v226, v244
	v_cvt_pk_bf16_f32 v218, v215, v219
	v_cvt_pk_bf16_f32 v219, v227, v245
	v_and_b32_e32 v220, 1, v232
	v_mul_u32_u24_e32 v220, 0x7f8, v220
	v_add_u32_e32 v220, v149, v220
	s_mov_b32 vcc_lo, 0x55555555
	s_mov_b32 vcc_hi, 0x55555555
	v_cndmask_b32_dpp v208, v210, v204, vcc quad_perm:[1,0,3,2] row_mask:0xf bank_mask:0xf
	v_cndmask_b32_dpp v209, v211, v205, vcc quad_perm:[1,0,3,2] row_mask:0xf bank_mask:0xf
	v_cndmask_b32_dpp v216, v218, v206, vcc quad_perm:[1,0,3,2] row_mask:0xf bank_mask:0xf
	v_cndmask_b32_dpp v217, v219, v207, vcc quad_perm:[1,0,3,2] row_mask:0xf bank_mask:0xf
	s_not_b64 vcc, vcc
	v_cndmask_b32_dpp v210, v204, v210, vcc quad_perm:[1,0,3,2] row_mask:0xf bank_mask:0xf
	v_cndmask_b32_dpp v211, v205, v211, vcc quad_perm:[1,0,3,2] row_mask:0xf bank_mask:0xf
	v_cndmask_b32_dpp v218, v206, v218, vcc quad_perm:[1,0,3,2] row_mask:0xf bank_mask:0xf
	v_cndmask_b32_dpp v219, v207, v219, vcc quad_perm:[1,0,3,2] row_mask:0xf bank_mask:0xf
	global_store_dwordx4 v220, v[208:211], s[4:5]
	s_mov_b64 s[12:13], 0
	s_add_u32 s4, s18, 0x1000
	s_addc_u32 s5, s19, 0
	global_store_dwordx4 v220, v[216:219], s[4:5]

; __device__ __forceinline__ float row16_sum(float v) { v += dppf<0xB1>(v); v += dppf<0x4E>(v); v += dppf<0x141>(v); v += dppf<0x140>(v); return v; }
; __device__ __forceinline__ float frsq(float x) { return __builtin_amdgcn_rsqf(x); }
; __device__ __forceinline__ v2u pack4(const f32x4 v) { v2u r; r.x = pk2(v[0], v[1]); r.y = pk2(v[2], v[3]); return r; }
; __device__ __forceinline__ f32x4 unpack4(const v2u w) { f32x4 r; r[0] = bflo(w.x); r[1] = bfhi(w.x); r[2] = bflo(w.y); r[3] = bfhi(w.y); return r; }
; __device__ __forceinline__ const char* upin(const char* p) { asm volatile("" : "+s"(p)); return p; }
; __device__ __forceinline__ char* upin(char* p) { asm volatile("" : "+s"(p)); return p; }
; template <bool GDN> __device__ __forceinline__ void scan_finish(const Frame& F, int b, int h, int dir, const ScanLane& L, int s, float* PEND, const f32x4 (&Oin)[4], const ScanFin& f) {
;     const int cidx = dir ? (s < 4 ? 3 - s : 39 - s) : s; const int row0 = chunk_row0(b, cidx);
;     if (scan_first(s)) {
;         char* pp = upin((char*)PEND + (size_t)((b * 4 + h) * 36 + cidx) * 16384);
; #pragma unroll
;         for (int pr = 0; pr < 2; ++pr) { const v2u a = pack4(Oin[2 * pr]), bq = pack4(Oin[2 * pr + 1]); v4u o; o.x = a.x; o.y = a.y; o.z = bq.x; o.w = bq.y; stu<v4u>(pp + pr * 1024, L.pend, o); }
;     } else {
;         f32x4 O[4]; float ss[4] = {0.f, 0.f, 0.f, 0.f};
; #pragma unroll
;         for (int t = 0; t < 4; ++t)
;             { const f32x4 pv = unpack4(f.pend[t]);
; #pragma unroll
;             for (int i = 0; i < 4; ++i) { O[t][i] = Oin[t][i] + pv[i]; ss[i] += O[t][i] * O[t][i]; } }
; #pragma unroll
;         for (int i = 0; i < 4; ++i) ss[i] = frsq(row16_sum(ss[i]) * (1.f / 64.f) + EPS);
;         char* mp = (char*)F.MIX + ((size_t)row0 * 1024 + (GDN ? 0 : 768) + h * 64) * 2;
; #pragma unroll
;         for (int i = 0; i < 4; ++i) { const f32x4 g = unpack4(f.gz[i]); f32x4 ov;
; #pragma unroll
;             for (int t = 0; t < 4; ++t) ov[t] = O[t][i] * ss[i] * g[t];
;             stu<v2u>(upin(mp + i * 2048), L.mix, pack4(ov)); }
.LBB0_520:
	s_cmp_gt_u32 s23, 3
	s_cselect_b32 s5, 39, 3
	s_add_i32 s5, s5, s22
	s_add_i32 s1, s5, 3
	s_and_b64 s[6:7], s[90:91], exec
	s_cselect_b32 s1, s23, s1
	s_cmp_lt_u32 s4, 5
	s_cselect_b32 s3, 2, 20
	s_cmp_lt_u32 s23, s3
	s_mov_b64 s[12:13], -1
	s_cbranch_scc1 .LBB0_522
	s_cmp_lt_i32 s1, 4
	s_cselect_b32 s3, s25, s24
	s_lshl_b32 s6, s1, 6
	s_add_i32 s6, s3, s6
	s_ashr_i32 s7, s6, 31
	s_lshl_b64 s[6:7], s[6:7], 11
	s_add_u32 s18, s26, s6
	s_addc_u32 s19, s27, s7
	s_mov_b64 s[6:7], s[18:19]
	v_lshlrev_b32_e32 v208, 16, v2
	v_and_b32_e32 v209, 0xffff0000, v2
	v_lshlrev_b32_e32 v210, 16, v3
	v_and_b32_e32 v211, 0xffff0000, v3
	v_pk_add_f32 v[212:213], v[130:131], v[208:209]
	v_pk_add_f32 v[214:215], v[132:133], v[210:211]
	v_pk_mul_f32 v[204:205], v[212:213], v[212:213]
	v_pk_mul_f32 v[206:207], v[214:215], v[214:215]
	v_lshlrev_b32_e32 v208, 16, v4
	v_and_b32_e32 v209, 0xffff0000, v4
	v_lshlrev_b32_e32 v210, 16, v5
	v_and_b32_e32 v211, 0xffff0000, v5
	v_pk_add_f32 v[216:217], v[134:135], v[208:209]
	v_pk_add_f32 v[218:219], v[136:137], v[210:211]
	v_pk_fma_f32 v[204:205], v[216:217], v[216:217], v[204:205]
	v_pk_fma_f32 v[206:207], v[218:219], v[218:219], v[206:207]
	v_lshlrev_b32_e32 v208, 16, v6
	v_and_b32_e32 v209, 0xffff0000, v6
	v_lshlrev_b32_e32 v210, 16, v7
	v_and_b32_e32 v211, 0xffff0000, v7
	v_pk_add_f32 v[224:225], v[138:139], v[208:209]
	v_pk_add_f32 v[226:227], v[140:141], v[210:211]
	v_pk_fma_f32 v[204:205], v[224:225], v[224:225], v[204:205]
	v_pk_fma_f32 v[206:207], v[226:227], v[226:227], v[206:207]
	v_lshlrev_b32_e32 v208, 16, v8
	v_and_b32_e32 v209, 0xffff0000, v8
	v_lshlrev_b32_e32 v210, 16, v9
	v_and_b32_e32 v211, 0xffff0000, v9
	v_pk_add_f32 v[242:243], v[142:143], v[208:209]
	v_pk_add_f32 v[244:245], v[144:145], v[210:211]
	v_pk_fma_f32 v[204:205], v[242:243], v[242:243], v[204:205]
	v_pk_fma_f32 v[206:207], v[244:245], v[244:245], v[206:207]
	s_nop 1
	v_add_f32_dpp v204, v204, v204 quad_perm:[1,0,3,2] row_mask:0xf bank_mask:0xf bound_ctrl:1
	v_add_f32_dpp v205, v205, v205 quad_perm:[1,0,3,2] row_mask:0xf bank_mask:0xf bound_ctrl:1
	v_add_f32_dpp v206, v206, v206 quad_perm:[1,0,3,2] row_mask:0xf bank_mask:0xf bound_ctrl:1
	v_add_f32_dpp v207, v207, v207 quad_perm:[1,0,3,2] row_mask:0xf bank_mask:0xf bound_ctrl:1
	v_add_f32_dpp v204, v204, v204 quad_perm:[2,3,0,1] row_mask:0xf bank_mask:0xf bound_ctrl:1
	v_add_f32_dpp v205, v205, v205 quad_perm:[2,3,0,1] row_mask:0xf bank_mask:0xf bound_ctrl:1
	v_add_f32_dpp v206, v206, v206 quad_perm:[2,3,0,1] row_mask:0xf bank_mask:0xf bound_ctrl:1
	v_add_f32_dpp v207, v207, v207 quad_perm:[2,3,0,1] row_mask:0xf bank_mask:0xf bound_ctrl:1
	v_add_f32_dpp v204, v204, v204 row_half_mirror row_mask:0xf bank_mask:0xf bound_ctrl:1
	v_add_f32_dpp v205, v205, v205 row_half_mirror row_mask:0xf bank_mask:0xf bound_ctrl:1
	v_add_f32_dpp v206, v206, v206 row_half_mirror row_mask:0xf bank_mask:0xf bound_ctrl:1
	v_add_f32_dpp v207, v207, v207 row_half_mirror row_mask:0xf bank_mask:0xf bound_ctrl:1
	v_add_f32_dpp v204, v204, v204 row_mirror row_mask:0xf bank_mask:0xf bound_ctrl:1
	v_add_f32_dpp v205, v205, v205 row_mirror row_mask:0xf bank_mask:0xf bound_ctrl:1
	v_add_f32_dpp v206, v206, v206 row_mirror row_mask:0xf bank_mask:0xf bound_ctrl:1
	v_add_f32_dpp v207, v207, v207 row_mirror row_mask:0xf bank_mask:0xf bound_ctrl:1
	v_fmamk_f32 v204, v204, 0x3c800000, v231
	v_fmamk_f32 v205, v205, 0x3c800000, v231
	v_fmamk_f32 v206, v206, 0x3c800000, v231
	v_fmamk_f32 v207, v207, 0x3c800000, v231
	v_rsq_f32_e32 v204, v204
	v_rsq_f32_e32 v205, v205
	v_rsq_f32_e32 v206, v206
	v_rsq_f32_e32 v207, v207
	v_lshlrev_b32_e32 v208, 16, v156
	v_lshlrev_b32_e32 v209, 16, v158
	v_lshlrev_b32_e32 v210, 16, v160
	v_lshlrev_b32_e32 v211, 16, v162
	v_pk_mul_f32 v[212:213], v[212:213], v[204:205]
	v_pk_mul_f32 v[214:215], v[214:215], v[206:207]
	v_pk_mul_f32 v[212:213], v[212:213], v[208:209]
	v_pk_mul_f32 v[214:215], v[214:215], v[210:211]
	v_and_b32_e32 v208, 0xffff0000, v156
	v_and_b32_e32 v209, 0xffff0000, v158
	v_and_b32_e32 v210, 0xffff0000, v160
	v_and_b32_e32 v211, 0xffff0000, v162
	v_pk_mul_f32 v[216:217], v[216:217], v[204:205]
	v_pk_mul_f32 v[218:219], v[218:219], v[206:207]
	v_pk_mul_f32 v[216:217], v[216:217], v[208:209]
	v_pk_mul_f32 v[218:219], v[218:219], v[210:211]
	v_lshlrev_b32_e32 v208, 16, v157
	v_lshlrev_b32_e32 v209, 16, v159
	v_lshlrev_b32_e32 v210, 16, v161
	v_lshlrev_b32_e32 v211, 16, v163
	v_pk_mul_f32 v[224:225], v[224:225], v[204:205]
	v_pk_mul_f32 v[226:227], v[226:227], v[206:207]
	v_pk_mul_f32 v[224:225], v[224:225], v[208:209]
	v_pk_mul_f32 v[226:227], v[226:227], v[210:211]
	v_and_b32_e32 v208, 0xffff0000, v157
	v_and_b32_e32 v209, 0xffff0000, v159
	v_and_b32_e32 v210, 0xffff0000, v161
	v_and_b32_e32 v211, 0xffff0000, v163
	v_pk_mul_f32 v[242:243], v[242:243], v[204:205]
	v_pk_mul_f32 v[244:245], v[244:245], v[206:207]
	v_pk_mul_f32 v[242:243], v[242:243], v[208:209]
	v_pk_mul_f32 v[244:245], v[244:245], v[210:211]
	v_cvt_pk_bf16_f32 v204, v212, v216
	v_cvt_pk_bf16_f32 v205, v224, v242
	v_cvt_pk_bf16_f32 v210, v213, v217
	v_cvt_pk_bf16_f32 v211, v225, v243
	v_cvt_pk_bf16_f32 v206, v214, v218
	v_cvt_pk_bf16_f32 v207, v226, v244
	v_cvt_pk_bf16_f32 v218, v215, v219
	v_cvt_pk_bf16_f32 v219, v227, v245
	v_and_b32_e32 v220, 1, v232
	v_mul_u32_u24_e32 v220, 0x7f8, v220
	v_add_u32_e32 v220, v40, v220
	s_mov_b32 vcc_lo, 0x55555555
	s_mov_b32 vcc_hi, 0x55555555
	v_cndmask_b32_dpp v208, v210, v204, vcc quad_perm:[1,0,3,2] row_mask:0xf bank_mask:0xf
	v_cndmask_b32_dpp v209, v211, v205, vcc quad_perm:[1,0,3,2] row_mask:0xf bank_mask:0xf
	v_cndmask_b32_dpp v216, v218, v206, vcc quad_perm:[1,0,3,2] row_mask:0xf bank_mask:0xf
	v_cndmask_b32_dpp v217, v219, v207, vcc quad_perm:[1,0,3,2] row_mask:0xf bank_mask:0xf
	s_not_b64 vcc, vcc
	v_cndmask_b32_dpp v210, v204, v210, vcc quad_perm:[1,0,3,2] row_mask:0xf bank_mask:0xf
	v_cndmask_b32_dpp v211, v205, v211, vcc quad_perm:[1,0,3,2] row_mask:0xf bank_mask:0xf
	v_cndmask_b32_dpp v218, v206, v218, vcc quad_perm:[1,0,3,2] row_mask:0xf bank_mask:0xf
	v_cndmask_b32_dpp v219, v207, v219, vcc quad_perm:[1,0,3,2] row_mask:0xf bank_mask:0xf
	global_store_dwordx4 v220, v[208:211], s[6:7]
	s_mov_b64 s[12:13], 0
	s_add_u32 s6, s18, 0x1000
	s_addc_u32 s7, s19, 0
	global_store_dwordx4 v220, v[216:219], s[6:7]

; __device__ __forceinline__ float row16_sum(float v) { v += dppf<0xB1>(v); v += dppf<0x4E>(v); v += dppf<0x141>(v); v += dppf<0x140>(v); return v; }
; __device__ __forceinline__ float frsq(float x) { return __builtin_amdgcn_rsqf(x); }
; __device__ __forceinline__ v2u pack4(const f32x4 v) { v2u r; r.x = pk2(v[0], v[1]); r.y = pk2(v[2], v[3]); return r; }
; __device__ __forceinline__ f32x4 unpack4(const v2u w) { f32x4 r; r[0] = bflo(w.x); r[1] = bfhi(w.x); r[2] = bflo(w.y); r[3] = bfhi(w.y); return r; }
; __device__ __forceinline__ const char* upin(const char* p) { asm volatile("" : "+s"(p)); return p; }
; __device__ __forceinline__ char* upin(char* p) { asm volatile("" : "+s"(p)); return p; }
; template <bool GDN> __device__ __forceinline__ void scan_finish(const Frame& F, int b, int h, int dir, const ScanLane& L, int s, float* PEND, const f32x4 (&Oin)[4], const ScanFin& f) {
;     const int cidx = dir ? (s < 4 ? 3 - s : 39 - s) : s; const int row0 = chunk_row0(b, cidx);
;     if (scan_first(s)) {
;         char* pp = upin((char*)PEND + (size_t)((b * 4 + h) * 36 + cidx) * 16384);
; #pragma unroll
;         for (int pr = 0; pr < 2; ++pr) { const v2u a = pack4(Oin[2 * pr]), bq = pack4(Oin[2 * pr + 1]); v4u o; o.x = a.x; o.y = a.y; o.z = bq.x; o.w = bq.y; stu<v4u>(pp + pr * 1024, L.pend, o); }
;     } else {
;         f32x4 O[4]; float ss[4] = {0.f, 0.f, 0.f, 0.f};
; #pragma unroll
;         for (int t = 0; t < 4; ++t)
;             { const f32x4 pv = unpack4(f.pend[t]);
; #pragma unroll
;             for (int i = 0; i < 4; ++i) { O[t][i] = Oin[t][i] + pv[i]; ss[i] += O[t][i] * O[t][i]; } }
; #pragma unroll
;         for (int i = 0; i < 4; ++i) ss[i] = frsq(row16_sum(ss[i]) * (1.f / 64.f) + EPS);
;         char* mp = (char*)F.MIX + ((size_t)row0 * 1024 + (GDN ? 0 : 768) + h * 64) * 2;
; #pragma unroll
;         for (int i = 0; i < 4; ++i) { const f32x4 g = unpack4(f.gz[i]); f32x4 ov;
; #pragma unroll
;             for (int t = 0; t < 4; ++t) ov[t] = O[t][i] * ss[i] * g[t];
;             stu<v2u>(upin(mp + i * 2048), L.mix, pack4(ov)); }
;     ...
;     __syncthreads();
;     if (s > 0) {
;         const int sp = s - 1;
;         if (sp == 20 || sp == 2) { asm volatile("s_waitcnt vmcnt(0)" ::: "memory"); scan_fin_load<GDN>(F, b, h, dir, L, sp, PEND, fin); }
;         if (!nofin) scan_finish<GDN>(F, b, h, dir, L, sp, PEND, Oprev, fin);
.LBB0_537:
	s_cmp_gt_u32 s23, 2
	s_cselect_b32 s6, 20, 2
	s_cmp_lt_u32 s4, s6
	s_mov_b64 s[10:11], -1
	s_waitcnt lgkmcnt(0)
	s_barrier
	s_cbranch_scc1 .LBB0_540
	s_cmp_lt_i32 s5, 4
	s_cselect_b32 s4, s25, s24
	s_lshl_b32 s6, s5, 6
	s_add_i32 s6, s4, s6
	s_ashr_i32 s7, s6, 31
	s_lshl_b64 s[6:7], s[6:7], 11
	s_add_u32 s10, s26, s6
	s_addc_u32 s11, s27, s7
	s_mov_b64 s[6:7], s[10:11]
	v_lshlrev_b32_e32 v208, 16, v10
	v_and_b32_e32 v209, 0xffff0000, v10
	v_lshlrev_b32_e32 v210, 16, v11
	v_and_b32_e32 v211, 0xffff0000, v11
	v_pk_add_f32 v[212:213], v[130:131], v[208:209]
	v_pk_add_f32 v[214:215], v[132:133], v[210:211]
	v_pk_mul_f32 v[204:205], v[212:213], v[212:213]
	v_pk_mul_f32 v[206:207], v[214:215], v[214:215]
	v_lshlrev_b32_e32 v208, 16, v12
	v_and_b32_e32 v209, 0xffff0000, v12
	v_lshlrev_b32_e32 v210, 16, v13
	v_and_b32_e32 v211, 0xffff0000, v13
	v_pk_add_f32 v[216:217], v[134:135], v[208:209]
	v_pk_add_f32 v[218:219], v[136:137], v[210:211]
	v_pk_fma_f32 v[204:205], v[216:217], v[216:217], v[204:205]
	v_pk_fma_f32 v[206:207], v[218:219], v[218:219], v[206:207]
	v_lshlrev_b32_e32 v208, 16, v14
	v_and_b32_e32 v209, 0xffff0000, v14
	v_lshlrev_b32_e32 v210, 16, v15
	v_and_b32_e32 v211, 0xffff0000, v15
	v_pk_add_f32 v[224:225], v[138:139], v[208:209]
	v_pk_add_f32 v[226:227], v[140:141], v[210:211]
	v_pk_fma_f32 v[204:205], v[224:225], v[224:225], v[204:205]
	v_pk_fma_f32 v[206:207], v[226:227], v[226:227], v[206:207]
	v_lshlrev_b32_e32 v208, 16, v16
	v_and_b32_e32 v209, 0xffff0000, v16
	v_lshlrev_b32_e32 v210, 16, v17
	v_and_b32_e32 v211, 0xffff0000, v17
	v_pk_add_f32 v[242:243], v[142:143], v[208:209]
	v_pk_add_f32 v[244:245], v[144:145], v[210:211]
	v_pk_fma_f32 v[204:205], v[242:243], v[242:243], v[204:205]
	v_pk_fma_f32 v[206:207], v[244:245], v[244:245], v[206:207]
	s_nop 1
	v_add_f32_dpp v204, v204, v204 quad_perm:[1,0,3,2] row_mask:0xf bank_mask:0xf bound_ctrl:1
	v_add_f32_dpp v205, v205, v205 quad_perm:[1,0,3,2] row_mask:0xf bank_mask:0xf bound_ctrl:1
	v_add_f32_dpp v206, v206, v206 quad_perm:[1,0,3,2] row_mask:0xf bank_mask:0xf bound_ctrl:1
	v_add_f32_dpp v207, v207, v207 quad_perm:[1,0,3,2] row_mask:0xf bank_mask:0xf bound_ctrl:1
	v_add_f32_dpp v204, v204, v204 quad_perm:[2,3,0,1] row_mask:0xf bank_mask:0xf bound_ctrl:1
	v_add_f32_dpp v205, v205, v205 quad_perm:[2,3,0,1] row_mask:0xf bank_mask:0xf bound_ctrl:1
	v_add_f32_dpp v206, v206, v206 quad_perm:[2,3,0,1] row_mask:0xf bank_mask:0xf bound_ctrl:1
	v_add_f32_dpp v207, v207, v207 quad_perm:[2,3,0,1] row_mask:0xf bank_mask:0xf bound_ctrl:1
	v_add_f32_dpp v204, v204, v204 row_half_mirror row_mask:0xf bank_mask:0xf bound_ctrl:1
	v_add_f32_dpp v205, v205, v205 row_half_mirror row_mask:0xf bank_mask:0xf bound_ctrl:1
	v_add_f32_dpp v206, v206, v206 row_half_mirror row_mask:0xf bank_mask:0xf bound_ctrl:1
	v_add_f32_dpp v207, v207, v207 row_half_mirror row_mask:0xf bank_mask:0xf bound_ctrl:1
	v_add_f32_dpp v204, v204, v204 row_mirror row_mask:0xf bank_mask:0xf bound_ctrl:1
	v_add_f32_dpp v205, v205, v205 row_mirror row_mask:0xf bank_mask:0xf bound_ctrl:1
	v_add_f32_dpp v206, v206, v206 row_mirror row_mask:0xf bank_mask:0xf bound_ctrl:1
	v_add_f32_dpp v207, v207, v207 row_mirror row_mask:0xf bank_mask:0xf bound_ctrl:1
	v_fmamk_f32 v204, v204, 0x3c800000, v231
	v_fmamk_f32 v205, v205, 0x3c800000, v231
	v_fmamk_f32 v206, v206, 0x3c800000, v231
	v_fmamk_f32 v207, v207, 0x3c800000, v231
	v_rsq_f32_e32 v204, v204
	v_rsq_f32_e32 v205, v205
	v_rsq_f32_e32 v206, v206
	v_rsq_f32_e32 v207, v207
	v_lshlrev_b32_e32 v208, 16, v164
	v_lshlrev_b32_e32 v209, 16, v178
	v_lshlrev_b32_e32 v210, 16, v180
	v_lshlrev_b32_e32 v211, 16, v182
	v_pk_mul_f32 v[212:213], v[212:213], v[204:205]
	v_pk_mul_f32 v[214:215], v[214:215], v[206:207]
	v_pk_mul_f32 v[212:213], v[212:213], v[208:209]
	v_pk_mul_f32 v[214:215], v[214:215], v[210:211]
	v_and_b32_e32 v208, 0xffff0000, v164
	v_and_b32_e32 v209, 0xffff0000, v178
	v_and_b32_e32 v210, 0xffff0000, v180
	v_and_b32_e32 v211, 0xffff0000, v182
	v_pk_mul_f32 v[216:217], v[216:217], v[204:205]
	v_pk_mul_f32 v[218:219], v[218:219], v[206:207]
	v_pk_mul_f32 v[216:217], v[216:217], v[208:209]
	v_pk_mul_f32 v[218:219], v[218:219], v[210:211]
	v_lshlrev_b32_e32 v208, 16, v165
	v_lshlrev_b32_e32 v209, 16, v179
	v_lshlrev_b32_e32 v210, 16, v181
	v_lshlrev_b32_e32 v211, 16, v183
	v_pk_mul_f32 v[224:225], v[224:225], v[204:205]
	v_pk_mul_f32 v[226:227], v[226:227], v[206:207]
	v_pk_mul_f32 v[224:225], v[224:225], v[208:209]
	v_pk_mul_f32 v[226:227], v[226:227], v[210:211]
	v_and_b32_e32 v208, 0xffff0000, v165
	v_and_b32_e32 v209, 0xffff0000, v179
	v_and_b32_e32 v210, 0xffff0000, v181
	v_and_b32_e32 v211, 0xffff0000, v183
	v_pk_mul_f32 v[242:243], v[242:243], v[204:205]
	v_pk_mul_f32 v[244:245], v[244:245], v[206:207]
	v_pk_mul_f32 v[242:243], v[242:243], v[208:209]
	v_pk_mul_f32 v[244:245], v[244:245], v[210:211]
	v_cvt_pk_bf16_f32 v204, v212, v216
	v_cvt_pk_bf16_f32 v205, v224, v242
	v_cvt_pk_bf16_f32 v210, v213, v217
	v_cvt_pk_bf16_f32 v211, v225, v243
	v_cvt_pk_bf16_f32 v206, v214, v218
	v_cvt_pk_bf16_f32 v207, v226, v244
	v_cvt_pk_bf16_f32 v218, v215, v219
	v_cvt_pk_bf16_f32 v219, v227, v245
	v_and_b32_e32 v220, 1, v232
	v_mul_u32_u24_e32 v220, 0x7f8, v220
	v_add_u32_e32 v220, v146, v220
	s_mov_b32 vcc_lo, 0x55555555
	s_mov_b32 vcc_hi, 0x55555555
	v_cndmask_b32_dpp v208, v210, v204, vcc quad_perm:[1,0,3,2] row_mask:0xf bank_mask:0xf
	v_cndmask_b32_dpp v209, v211, v205, vcc quad_perm:[1,0,3,2] row_mask:0xf bank_mask:0xf
	v_cndmask_b32_dpp v216, v218, v206, vcc quad_perm:[1,0,3,2] row_mask:0xf bank_mask:0xf
	v_cndmask_b32_dpp v217, v219, v207, vcc quad_perm:[1,0,3,2] row_mask:0xf bank_mask:0xf
	s_not_b64 vcc, vcc
	v_cndmask_b32_dpp v210, v204, v210, vcc quad_perm:[1,0,3,2] row_mask:0xf bank_mask:0xf
	v_cndmask_b32_dpp v211, v205, v211, vcc quad_perm:[1,0,3,2] row_mask:0xf bank_mask:0xf
	v_cndmask_b32_dpp v218, v206, v218, vcc quad_perm:[1,0,3,2] row_mask:0xf bank_mask:0xf
	v_cndmask_b32_dpp v219, v207, v219, vcc quad_perm:[1,0,3,2] row_mask:0xf bank_mask:0xf
	global_store_dwordx4 v220, v[208:211], s[6:7]
	s_add_u32 s6, s10, 0x1000
	s_addc_u32 s7, s11, 0
	global_store_dwordx4 v220, v[216:219], s[6:7]
	s_add_u32 s6, s10, 0x1800
	s_addc_u32 s7, s11, 0
	s_cbranch_execz .LBB0_541

;     ...
;     if (s > 0) {
;         const int sp = s - 1;
;         if (sp == 20 || sp == 2) { asm volatile("s_waitcnt vmcnt(0)" ::: "memory"); scan_fin_load<GDN>(F, b, h, dir, L, sp, PEND, fin); }
;         if (!nofin) scan_finish<GDN>(F, b, h, dir, L, sp, PEND, Oprev, fin);
.LBB0_551:
.LBB0_552:
	s_cmp_eq_u32 s23, 0
	s_cselect_b64 s[10:11], -1, 0
	s_cmp_lg_u32 s23, 0
	s_cselect_b64 s[12:13], -1, 0

; __device__ __forceinline__ float row16_sum(float v) { v += dppf<0xB1>(v); v += dppf<0x4E>(v); v += dppf<0x141>(v); v += dppf<0x140>(v); return v; }
; __device__ __forceinline__ float frsq(float x) { return __builtin_amdgcn_rsqf(x); }
; __device__ __forceinline__ v2u pack4(const f32x4 v) { v2u r; r.x = pk2(v[0], v[1]); r.y = pk2(v[2], v[3]); return r; }
; __device__ __forceinline__ f32x4 unpack4(const v2u w) { f32x4 r; r[0] = bflo(w.x); r[1] = bfhi(w.x); r[2] = bflo(w.y); r[3] = bfhi(w.y); return r; }
; __device__ __forceinline__ const char* upin(const char* p) { asm volatile("" : "+s"(p)); return p; }
; __device__ __forceinline__ char* upin(char* p) { asm volatile("" : "+s"(p)); return p; }
; template <bool GDN> __device__ __forceinline__ void scan_finish(const Frame& F, int b, int h, int dir, const ScanLane& L, int s, float* PEND, const f32x4 (&Oin)[4], const ScanFin& f) {
;     const int cidx = dir ? (s < 4 ? 3 - s : 39 - s) : s; const int row0 = chunk_row0(b, cidx);
;     if (scan_first(s)) {
;         char* pp = upin((char*)PEND + (size_t)((b * 4 + h) * 36 + cidx) * 16384);
; #pragma unroll
;         for (int pr = 0; pr < 2; ++pr) { const v2u a = pack4(Oin[2 * pr]), bq = pack4(Oin[2 * pr + 1]); v4u o; o.x = a.x; o.y = a.y; o.z = bq.x; o.w = bq.y; stu<v4u>(pp + pr * 1024, L.pend, o); }
;     } else {
;         f32x4 O[4]; float ss[4] = {0.f, 0.f, 0.f, 0.f};
; #pragma unroll
;         for (int t = 0; t < 4; ++t)
;             { const f32x4 pv = unpack4(f.pend[t]);
; #pragma unroll
;             for (int i = 0; i < 4; ++i) { O[t][i] = Oin[t][i] + pv[i]; ss[i] += O[t][i] * O[t][i]; } }
; #pragma unroll
;         for (int i = 0; i < 4; ++i) ss[i] = frsq(row16_sum(ss[i]) * (1.f / 64.f) + EPS);
;         char* mp = (char*)F.MIX + ((size_t)row0 * 1024 + (GDN ? 0 : 768) + h * 64) * 2;
; #pragma unroll
;         for (int i = 0; i < 4; ++i) { const f32x4 g = unpack4(f.gz[i]); f32x4 ov;
; #pragma unroll
;             for (int t = 0; t < 4; ++t) ov[t] = O[t][i] * ss[i] * g[t];
;             stu<v2u>(upin(mp + i * 2048), L.mix, pack4(ov)); }
.LBB0_568:
	s_cmp_lt_i32 s4, 4
	s_cselect_b32 s3, s25, s24
	s_lshl_b32 s5, s4, 6
	s_add_i32 s6, s3, s5
	s_ashr_i32 s7, s6, 31
	s_lshl_b64 s[6:7], s[6:7], 11
	s_add_u32 s10, s26, s6
	s_addc_u32 s11, s27, s7
	s_mov_b64 s[6:7], s[10:11]
	v_lshlrev_b32_e32 v208, 16, v2
	v_and_b32_e32 v209, 0xffff0000, v2
	v_lshlrev_b32_e32 v210, 16, v3
	v_and_b32_e32 v211, 0xffff0000, v3
	v_pk_add_f32 v[212:213], v[130:131], v[208:209]
	v_pk_add_f32 v[214:215], v[132:133], v[210:211]
	v_pk_mul_f32 v[204:205], v[212:213], v[212:213]
	v_pk_mul_f32 v[206:207], v[214:215], v[214:215]
	v_lshlrev_b32_e32 v208, 16, v4
	v_and_b32_e32 v209, 0xffff0000, v4
	v_lshlrev_b32_e32 v210, 16, v5
	v_and_b32_e32 v211, 0xffff0000, v5
	v_pk_add_f32 v[216:217], v[134:135], v[208:209]
	v_pk_add_f32 v[218:219], v[136:137], v[210:211]
	v_pk_fma_f32 v[204:205], v[216:217], v[216:217], v[204:205]
	v_pk_fma_f32 v[206:207], v[218:219], v[218:219], v[206:207]
	v_lshlrev_b32_e32 v208, 16, v6
	v_and_b32_e32 v209, 0xffff0000, v6
	v_lshlrev_b32_e32 v210, 16, v7
	v_and_b32_e32 v211, 0xffff0000, v7
	v_pk_add_f32 v[224:225], v[138:139], v[208:209]
	v_pk_add_f32 v[226:227], v[140:141], v[210:211]
	v_pk_fma_f32 v[204:205], v[224:225], v[224:225], v[204:205]
	v_pk_fma_f32 v[206:207], v[226:227], v[226:227], v[206:207]
	v_lshlrev_b32_e32 v208, 16, v8
	v_and_b32_e32 v209, 0xffff0000, v8
	v_lshlrev_b32_e32 v210, 16, v9
	v_and_b32_e32 v211, 0xffff0000, v9
	v_pk_add_f32 v[242:243], v[142:143], v[208:209]
	v_pk_add_f32 v[244:245], v[144:145], v[210:211]
	v_pk_fma_f32 v[204:205], v[242:243], v[242:243], v[204:205]
	v_pk_fma_f32 v[206:207], v[244:245], v[244:245], v[206:207]
	s_nop 1
	v_add_f32_dpp v204, v204, v204 quad_perm:[1,0,3,2] row_mask:0xf bank_mask:0xf bound_ctrl:1
	v_add_f32_dpp v205, v205, v205 quad_perm:[1,0,3,2] row_mask:0xf bank_mask:0xf bound_ctrl:1
	v_add_f32_dpp v206, v206, v206 quad_perm:[1,0,3,2] row_mask:0xf bank_mask:0xf bound_ctrl:1
	v_add_f32_dpp v207, v207, v207 quad_perm:[1,0,3,2] row_mask:0xf bank_mask:0xf bound_ctrl:1
	v_add_f32_dpp v204, v204, v204 quad_perm:[2,3,0,1] row_mask:0xf bank_mask:0xf bound_ctrl:1
	v_add_f32_dpp v205, v205, v205 quad_perm:[2,3,0,1] row_mask:0xf bank_mask:0xf bound_ctrl:1
	v_add_f32_dpp v206, v206, v206 quad_perm:[2,3,0,1] row_mask:0xf bank_mask:0xf bound_ctrl:1
	v_add_f32_dpp v207, v207, v207 quad_perm:[2,3,0,1] row_mask:0xf bank_mask:0xf bound_ctrl:1
	v_add_f32_dpp v204, v204, v204 row_half_mirror row_mask:0xf bank_mask:0xf bound_ctrl:1
	v_add_f32_dpp v205, v205, v205 row_half_mirror row_mask:0xf bank_mask:0xf bound_ctrl:1
	v_add_f32_dpp v206, v206, v206 row_half_mirror row_mask:0xf bank_mask:0xf bound_ctrl:1
	v_add_f32_dpp v207, v207, v207 row_half_mirror row_mask:0xf bank_mask:0xf bound_ctrl:1
	v_add_f32_dpp v204, v204, v204 row_mirror row_mask:0xf bank_mask:0xf bound_ctrl:1
	v_add_f32_dpp v205, v205, v205 row_mirror row_mask:0xf bank_mask:0xf bound_ctrl:1
	v_add_f32_dpp v206, v206, v206 row_mirror row_mask:0xf bank_mask:0xf bound_ctrl:1
	v_add_f32_dpp v207, v207, v207 row_mirror row_mask:0xf bank_mask:0xf bound_ctrl:1
	v_fmamk_f32 v204, v204, 0x3c800000, v231
	v_fmamk_f32 v205, v205, 0x3c800000, v231
	v_fmamk_f32 v206, v206, 0x3c800000, v231
	v_fmamk_f32 v207, v207, 0x3c800000, v231
	v_rsq_f32_e32 v204, v204
	v_rsq_f32_e32 v205, v205
	v_rsq_f32_e32 v206, v206
	v_rsq_f32_e32 v207, v207
	v_lshlrev_b32_e32 v208, 16, v156
	v_lshlrev_b32_e32 v209, 16, v158
	v_lshlrev_b32_e32 v210, 16, v160
	v_lshlrev_b32_e32 v211, 16, v162
	v_pk_mul_f32 v[212:213], v[212:213], v[204:205]
	v_pk_mul_f32 v[214:215], v[214:215], v[206:207]
	v_pk_mul_f32 v[212:213], v[212:213], v[208:209]
	v_pk_mul_f32 v[214:215], v[214:215], v[210:211]
	v_and_b32_e32 v208, 0xffff0000, v156
	v_and_b32_e32 v209, 0xffff0000, v158
	v_and_b32_e32 v210, 0xffff0000, v160
	v_and_b32_e32 v211, 0xffff0000, v162
	v_pk_mul_f32 v[216:217], v[216:217], v[204:205]
	v_pk_mul_f32 v[218:219], v[218:219], v[206:207]
	v_pk_mul_f32 v[216:217], v[216:217], v[208:209]
	v_pk_mul_f32 v[218:219], v[218:219], v[210:211]
	v_lshlrev_b32_e32 v208, 16, v157
	v_lshlrev_b32_e32 v209, 16, v159
	v_lshlrev_b32_e32 v210, 16, v161
	v_lshlrev_b32_e32 v211, 16, v163
	v_pk_mul_f32 v[224:225], v[224:225], v[204:205]
	v_pk_mul_f32 v[226:227], v[226:227], v[206:207]
	v_pk_mul_f32 v[224:225], v[224:225], v[208:209]
	v_pk_mul_f32 v[226:227], v[226:227], v[210:211]
	v_and_b32_e32 v208, 0xffff0000, v157
	v_and_b32_e32 v209, 0xffff0000, v159
	v_and_b32_e32 v210, 0xffff0000, v161
	v_and_b32_e32 v211, 0xffff0000, v163
	v_pk_mul_f32 v[242:243], v[242:243], v[204:205]
	v_pk_mul_f32 v[244:245], v[244:245], v[206:207]
	v_pk_mul_f32 v[242:243], v[242:243], v[208:209]
	v_pk_mul_f32 v[244:245], v[244:245], v[210:211]
	v_cvt_pk_bf16_f32 v204, v212, v216
	v_cvt_pk_bf16_f32 v205, v224, v242
	v_cvt_pk_bf16_f32 v210, v213, v217
	v_cvt_pk_bf16_f32 v211, v225, v243
	v_cvt_pk_bf16_f32 v206, v214, v218
	v_cvt_pk_bf16_f32 v207, v226, v244
	v_cvt_pk_bf16_f32 v218, v215, v219
	v_cvt_pk_bf16_f32 v219, v227, v245
	v_and_b32_e32 v220, 1, v232
	v_mul_u32_u24_e32 v220, 0x7f8, v220
	v_add_u32_e32 v220, v28, v220
	s_mov_b32 vcc_lo, 0x55555555
	s_mov_b32 vcc_hi, 0x55555555
	v_cndmask_b32_dpp v208, v210, v204, vcc quad_perm:[1,0,3,2] row_mask:0xf bank_mask:0xf
	v_cndmask_b32_dpp v209, v211, v205, vcc quad_perm:[1,0,3,2] row_mask:0xf bank_mask:0xf
	v_cndmask_b32_dpp v216, v218, v206, vcc quad_perm:[1,0,3,2] row_mask:0xf bank_mask:0xf
	v_cndmask_b32_dpp v217, v219, v207, vcc quad_perm:[1,0,3,2] row_mask:0xf bank_mask:0xf
	s_not_b64 vcc, vcc
	v_cndmask_b32_dpp v210, v204, v210, vcc quad_perm:[1,0,3,2] row_mask:0xf bank_mask:0xf
	v_cndmask_b32_dpp v211, v205, v211, vcc quad_perm:[1,0,3,2] row_mask:0xf bank_mask:0xf
	v_cndmask_b32_dpp v218, v206, v218, vcc quad_perm:[1,0,3,2] row_mask:0xf bank_mask:0xf
	v_cndmask_b32_dpp v219, v207, v219, vcc quad_perm:[1,0,3,2] row_mask:0xf bank_mask:0xf
	global_store_dwordx4 v220, v[208:211], s[6:7]
	s_add_u32 s6, s10, 0x1000
	s_addc_u32 s7, s11, 0
	global_store_dwordx4 v220, v[216:219], s[6:7]
	s_add_u32 s6, s10, 0x1800
	s_addc_u32 s7, s11, 0
	s_cbranch_execz .LBB0_581

; __device__ __forceinline__ float row16_sum(float v) { v += dppf<0xB1>(v); v += dppf<0x4E>(v); v += dppf<0x141>(v); v += dppf<0x140>(v); return v; }
; __device__ __forceinline__ float frsq(float x) { return __builtin_amdgcn_rsqf(x); }
; __device__ __forceinline__ v2u pack4(const f32x4 v) { v2u r; r.x = pk2(v[0], v[1]); r.y = pk2(v[2], v[3]); return r; }
; __device__ __forceinline__ f32x4 unpack4(const v2u w) { f32x4 r; r[0] = bflo(w.x); r[1] = bfhi(w.x); r[2] = bflo(w.y); r[3] = bfhi(w.y); return r; }
; __device__ __forceinline__ const char* upin(const char* p) { asm volatile("" : "+s"(p)); return p; }
; __device__ __forceinline__ char* upin(char* p) { asm volatile("" : "+s"(p)); return p; }
; template <bool GDN> __device__ __forceinline__ void scan_finish(const Frame& F, int b, int h, int dir, const ScanLane& L, int s, float* PEND, const f32x4 (&Oin)[4], const ScanFin& f) {
;     const int cidx = dir ? (s < 4 ? 3 - s : 39 - s) : s; const int row0 = chunk_row0(b, cidx);
;     if (scan_first(s)) {
;         char* pp = upin((char*)PEND + (size_t)((b * 4 + h) * 36 + cidx) * 16384);
; #pragma unroll
;         for (int pr = 0; pr < 2; ++pr) { const v2u a = pack4(Oin[2 * pr]), bq = pack4(Oin[2 * pr + 1]); v4u o; o.x = a.x; o.y = a.y; o.z = bq.x; o.w = bq.y; stu<v4u>(pp + pr * 1024, L.pend, o); }
;     } else {
;         f32x4 O[4]; float ss[4] = {0.f, 0.f, 0.f, 0.f};
; #pragma unroll
;         for (int t = 0; t < 4; ++t)
;             { const f32x4 pv = unpack4(f.pend[t]);
; #pragma unroll
;             for (int i = 0; i < 4; ++i) { O[t][i] = Oin[t][i] + pv[i]; ss[i] += O[t][i] * O[t][i]; } }
; #pragma unroll
;         for (int i = 0; i < 4; ++i) ss[i] = frsq(row16_sum(ss[i]) * (1.f / 64.f) + EPS);
;         char* mp = (char*)F.MIX + ((size_t)row0 * 1024 + (GDN ? 0 : 768) + h * 64) * 2;
; #pragma unroll
;         for (int i = 0; i < 4; ++i) { const f32x4 g = unpack4(f.gz[i]); f32x4 ov;
; #pragma unroll
;             for (int t = 0; t < 4; ++t) ov[t] = O[t][i] * ss[i] * g[t];
;             stu<v2u>(upin(mp + i * 2048), L.mix, pack4(ov)); }
;     ...
;     __syncthreads();
;     if (s > 0) {
;         const int sp = s - 1;
;         if (sp == 20 || sp == 2) { asm volatile("s_waitcnt vmcnt(0)" ::: "memory"); scan_fin_load<GDN>(F, b, h, dir, L, sp, PEND, fin); }
;         if (!nofin) scan_finish<GDN>(F, b, h, dir, L, sp, PEND, Oprev, fin);
.LBB0_575:
	s_cmp_lt_u32 s0, 16
	s_mov_b64 s[10:11], -1
	s_waitcnt lgkmcnt(0)
	s_barrier
	s_cbranch_scc1 .LBB0_584
	s_cmp_lt_i32 s1, 4
	s_cselect_b32 s0, s25, s24
	s_lshl_b32 s4, s1, 6
	s_add_i32 s4, s0, s4
	s_ashr_i32 s5, s4, 31
	s_lshl_b64 s[4:5], s[4:5], 11
	s_add_u32 s10, s26, s4
	s_addc_u32 s11, s27, s5
	s_mov_b64 s[4:5], s[10:11]
	v_lshlrev_b32_e32 v208, 16, v10
	v_and_b32_e32 v209, 0xffff0000, v10
	v_lshlrev_b32_e32 v210, 16, v11
	v_and_b32_e32 v211, 0xffff0000, v11
	v_pk_add_f32 v[212:213], v[130:131], v[208:209]
	v_pk_add_f32 v[214:215], v[132:133], v[210:211]
	v_pk_mul_f32 v[204:205], v[212:213], v[212:213]
	v_pk_mul_f32 v[206:207], v[214:215], v[214:215]
	v_lshlrev_b32_e32 v208, 16, v12
	v_and_b32_e32 v209, 0xffff0000, v12
	v_lshlrev_b32_e32 v210, 16, v13
	v_and_b32_e32 v211, 0xffff0000, v13
	v_pk_add_f32 v[216:217], v[134:135], v[208:209]
	v_pk_add_f32 v[218:219], v[136:137], v[210:211]
	v_pk_fma_f32 v[204:205], v[216:217], v[216:217], v[204:205]
	v_pk_fma_f32 v[206:207], v[218:219], v[218:219], v[206:207]
	v_lshlrev_b32_e32 v208, 16, v14
	v_and_b32_e32 v209, 0xffff0000, v14
	v_lshlrev_b32_e32 v210, 16, v15
	v_and_b32_e32 v211, 0xffff0000, v15
	v_pk_add_f32 v[224:225], v[138:139], v[208:209]
	v_pk_add_f32 v[226:227], v[140:141], v[210:211]
	v_pk_fma_f32 v[204:205], v[224:225], v[224:225], v[204:205]
	v_pk_fma_f32 v[206:207], v[226:227], v[226:227], v[206:207]
	v_lshlrev_b32_e32 v208, 16, v16
	v_and_b32_e32 v209, 0xffff0000, v16
	v_lshlrev_b32_e32 v210, 16, v17
	v_and_b32_e32 v211, 0xffff0000, v17
	v_pk_add_f32 v[242:243], v[142:143], v[208:209]
	v_pk_add_f32 v[244:245], v[144:145], v[210:211]
	v_pk_fma_f32 v[204:205], v[242:243], v[242:243], v[204:205]
	v_pk_fma_f32 v[206:207], v[244:245], v[244:245], v[206:207]
	s_nop 1
	v_add_f32_dpp v204, v204, v204 quad_perm:[1,0,3,2] row_mask:0xf bank_mask:0xf bound_ctrl:1
	v_add_f32_dpp v205, v205, v205 quad_perm:[1,0,3,2] row_mask:0xf bank_mask:0xf bound_ctrl:1
	v_add_f32_dpp v206, v206, v206 quad_perm:[1,0,3,2] row_mask:0xf bank_mask:0xf bound_ctrl:1
	v_add_f32_dpp v207, v207, v207 quad_perm:[1,0,3,2] row_mask:0xf bank_mask:0xf bound_ctrl:1
	v_add_f32_dpp v204, v204, v204 quad_perm:[2,3,0,1] row_mask:0xf bank_mask:0xf bound_ctrl:1
	v_add_f32_dpp v205, v205, v205 quad_perm:[2,3,0,1] row_mask:0xf bank_mask:0xf bound_ctrl:1
	v_add_f32_dpp v206, v206, v206 quad_perm:[2,3,0,1] row_mask:0xf bank_mask:0xf bound_ctrl:1
	v_add_f32_dpp v207, v207, v207 quad_perm:[2,3,0,1] row_mask:0xf bank_mask:0xf bound_ctrl:1
	v_add_f32_dpp v204, v204, v204 row_half_mirror row_mask:0xf bank_mask:0xf bound_ctrl:1
	v_add_f32_dpp v205, v205, v205 row_half_mirror row_mask:0xf bank_mask:0xf bound_ctrl:1
	v_add_f32_dpp v206, v206, v206 row_half_mirror row_mask:0xf bank_mask:0xf bound_ctrl:1
	v_add_f32_dpp v207, v207, v207 row_half_mirror row_mask:0xf bank_mask:0xf bound_ctrl:1
	v_add_f32_dpp v204, v204, v204 row_mirror row_mask:0xf bank_mask:0xf bound_ctrl:1
	v_add_f32_dpp v205, v205, v205 row_mirror row_mask:0xf bank_mask:0xf bound_ctrl:1
	v_add_f32_dpp v206, v206, v206 row_mirror row_mask:0xf bank_mask:0xf bound_ctrl:1
	v_add_f32_dpp v207, v207, v207 row_mirror row_mask:0xf bank_mask:0xf bound_ctrl:1
	v_fmamk_f32 v204, v204, 0x3c800000, v231
	v_fmamk_f32 v205, v205, 0x3c800000, v231
	v_fmamk_f32 v206, v206, 0x3c800000, v231
	v_fmamk_f32 v207, v207, 0x3c800000, v231
	v_rsq_f32_e32 v204, v204
	v_rsq_f32_e32 v205, v205
	v_rsq_f32_e32 v206, v206
	v_rsq_f32_e32 v207, v207
	v_lshlrev_b32_e32 v208, 16, v164
	v_lshlrev_b32_e32 v209, 16, v178
	v_lshlrev_b32_e32 v210, 16, v180
	v_lshlrev_b32_e32 v211, 16, v182
	v_pk_mul_f32 v[212:213], v[212:213], v[204:205]
	v_pk_mul_f32 v[214:215], v[214:215], v[206:207]
	v_pk_mul_f32 v[212:213], v[212:213], v[208:209]
	v_pk_mul_f32 v[214:215], v[214:215], v[210:211]
	v_and_b32_e32 v208, 0xffff0000, v164
	v_and_b32_e32 v209, 0xffff0000, v178
	v_and_b32_e32 v210, 0xffff0000, v180
	v_and_b32_e32 v211, 0xffff0000, v182
	v_pk_mul_f32 v[216:217], v[216:217], v[204:205]
	v_pk_mul_f32 v[218:219], v[218:219], v[206:207]
	v_pk_mul_f32 v[216:217], v[216:217], v[208:209]
	v_pk_mul_f32 v[218:219], v[218:219], v[210:211]
	v_lshlrev_b32_e32 v208, 16, v165
	v_lshlrev_b32_e32 v209, 16, v179
	v_lshlrev_b32_e32 v210, 16, v181
	v_lshlrev_b32_e32 v211, 16, v183
	v_pk_mul_f32 v[224:225], v[224:225], v[204:205]
	v_pk_mul_f32 v[226:227], v[226:227], v[206:207]
	v_pk_mul_f32 v[224:225], v[224:225], v[208:209]
	v_pk_mul_f32 v[226:227], v[226:227], v[210:211]
	v_and_b32_e32 v208, 0xffff0000, v165
	v_and_b32_e32 v209, 0xffff0000, v179
	v_and_b32_e32 v210, 0xffff0000, v181
	v_and_b32_e32 v211, 0xffff0000, v183
	v_pk_mul_f32 v[242:243], v[242:243], v[204:205]
	v_pk_mul_f32 v[244:245], v[244:245], v[206:207]
	v_pk_mul_f32 v[242:243], v[242:243], v[208:209]
	v_pk_mul_f32 v[244:245], v[244:245], v[210:211]
	v_cvt_pk_bf16_f32 v204, v212, v216
	v_cvt_pk_bf16_f32 v205, v224, v242
	v_cvt_pk_bf16_f32 v210, v213, v217
	v_cvt_pk_bf16_f32 v211, v225, v243
	v_cvt_pk_bf16_f32 v206, v214, v218
	v_cvt_pk_bf16_f32 v207, v226, v244
	v_cvt_pk_bf16_f32 v218, v215, v219
	v_cvt_pk_bf16_f32 v219, v227, v245
	v_and_b32_e32 v220, 1, v232
	v_mul_u32_u24_e32 v220, 0x7f8, v220
	v_add_u32_e32 v220, v149, v220
	s_mov_b32 vcc_lo, 0x55555555
	s_mov_b32 vcc_hi, 0x55555555
	v_cndmask_b32_dpp v208, v210, v204, vcc quad_perm:[1,0,3,2] row_mask:0xf bank_mask:0xf
	v_cndmask_b32_dpp v209, v211, v205, vcc quad_perm:[1,0,3,2] row_mask:0xf bank_mask:0xf
	v_cndmask_b32_dpp v216, v218, v206, vcc quad_perm:[1,0,3,2] row_mask:0xf bank_mask:0xf
	v_cndmask_b32_dpp v217, v219, v207, vcc quad_perm:[1,0,3,2] row_mask:0xf bank_mask:0xf
	s_not_b64 vcc, vcc
	v_cndmask_b32_dpp v210, v204, v210, vcc quad_perm:[1,0,3,2] row_mask:0xf bank_mask:0xf
	v_cndmask_b32_dpp v211, v205, v211, vcc quad_perm:[1,0,3,2] row_mask:0xf bank_mask:0xf
	v_cndmask_b32_dpp v218, v206, v218, vcc quad_perm:[1,0,3,2] row_mask:0xf bank_mask:0xf
	v_cndmask_b32_dpp v219, v207, v219, vcc quad_perm:[1,0,3,2] row_mask:0xf bank_mask:0xf
	global_store_dwordx4 v220, v[208:211], s[4:5]
	s_add_u32 s4, s10, 0x1000
	s_addc_u32 s5, s11, 0
	global_store_dwordx4 v220, v[216:219], s[4:5]
	s_add_u32 s4, s10, 0x1800
	s_addc_u32 s5, s11, 0
	s_cbranch_execz .LBB0_585

; __device__ __forceinline__ float row16_sum(float v) { v += dppf<0xB1>(v); v += dppf<0x4E>(v); v += dppf<0x141>(v); v += dppf<0x140>(v); return v; }
; __device__ __forceinline__ float frsq(float x) { return __builtin_amdgcn_rsqf(x); }
; __device__ __forceinline__ v2u pack4(const f32x4 v) { v2u r; r.x = pk2(v[0], v[1]); r.y = pk2(v[2], v[3]); return r; }
; __device__ __forceinline__ f32x4 unpack4(const v2u w) { f32x4 r; r[0] = bflo(w.x); r[1] = bfhi(w.x); r[2] = bflo(w.y); r[3] = bfhi(w.y); return r; }
; __device__ __forceinline__ const char* upin(const char* p) { asm volatile("" : "+s"(p)); return p; }
; __device__ __forceinline__ char* upin(char* p) { asm volatile("" : "+s"(p)); return p; }
; template <bool GDN> __device__ __forceinline__ void scan_finish(const Frame& F, int b, int h, int dir, const ScanLane& L, int s, float* PEND, const f32x4 (&Oin)[4], const ScanFin& f) {
;     const int cidx = dir ? (s < 4 ? 3 - s : 39 - s) : s; const int row0 = chunk_row0(b, cidx);
;     if (scan_first(s)) {
;         char* pp = upin((char*)PEND + (size_t)((b * 4 + h) * 36 + cidx) * 16384);
; #pragma unroll
;         for (int pr = 0; pr < 2; ++pr) { const v2u a = pack4(Oin[2 * pr]), bq = pack4(Oin[2 * pr + 1]); v4u o; o.x = a.x; o.y = a.y; o.z = bq.x; o.w = bq.y; stu<v4u>(pp + pr * 1024, L.pend, o); }
;     } else {
;         f32x4 O[4]; float ss[4] = {0.f, 0.f, 0.f, 0.f};
; #pragma unroll
;         for (int t = 0; t < 4; ++t)
;             { const f32x4 pv = unpack4(f.pend[t]);
; #pragma unroll
;             for (int i = 0; i < 4; ++i) { O[t][i] = Oin[t][i] + pv[i]; ss[i] += O[t][i] * O[t][i]; } }
; #pragma unroll
;         for (int i = 0; i < 4; ++i) ss[i] = frsq(row16_sum(ss[i]) * (1.f / 64.f) + EPS);
;         char* mp = (char*)F.MIX + ((size_t)row0 * 1024 + (GDN ? 0 : 768) + h * 64) * 2;
; #pragma unroll
;         for (int i = 0; i < 4; ++i) { const f32x4 g = unpack4(f.gz[i]); f32x4 ov;
; #pragma unroll
;             for (int t = 0; t < 4; ++t) ov[t] = O[t][i] * ss[i] * g[t];
;             stu<v2u>(upin(mp + i * 2048), L.mix, pack4(ov)); }
.LBB0_602:
	s_cmp_lt_i32 s0, 4
	s_cselect_b32 s1, s25, s24
	s_lshl_b32 s3, s0, 6
	s_add_i32 s4, s1, s3
	s_ashr_i32 s5, s4, 31
	s_lshl_b64 s[4:5], s[4:5], 11
	s_add_u32 s10, s26, s4
	s_addc_u32 s11, s27, s5
	s_mov_b64 s[4:5], s[10:11]
	v_lshlrev_b32_e32 v208, 16, v2
	v_and_b32_e32 v209, 0xffff0000, v2
	v_lshlrev_b32_e32 v210, 16, v3
	v_and_b32_e32 v211, 0xffff0000, v3
	v_pk_add_f32 v[212:213], v[130:131], v[208:209]
	v_pk_add_f32 v[214:215], v[132:133], v[210:211]
	v_pk_mul_f32 v[204:205], v[212:213], v[212:213]
	v_pk_mul_f32 v[206:207], v[214:215], v[214:215]
	v_lshlrev_b32_e32 v208, 16, v4
	v_and_b32_e32 v209, 0xffff0000, v4
	v_lshlrev_b32_e32 v210, 16, v5
	v_and_b32_e32 v211, 0xffff0000, v5
	v_pk_add_f32 v[216:217], v[134:135], v[208:209]
	v_pk_add_f32 v[218:219], v[136:137], v[210:211]
	v_pk_fma_f32 v[204:205], v[216:217], v[216:217], v[204:205]
	v_pk_fma_f32 v[206:207], v[218:219], v[218:219], v[206:207]
	v_lshlrev_b32_e32 v208, 16, v6
	v_and_b32_e32 v209, 0xffff0000, v6
	v_lshlrev_b32_e32 v210, 16, v7
	v_and_b32_e32 v211, 0xffff0000, v7
	v_pk_add_f32 v[224:225], v[138:139], v[208:209]
	v_pk_add_f32 v[226:227], v[140:141], v[210:211]
	v_pk_fma_f32 v[204:205], v[224:225], v[224:225], v[204:205]
	v_pk_fma_f32 v[206:207], v[226:227], v[226:227], v[206:207]
	v_lshlrev_b32_e32 v208, 16, v8
	v_and_b32_e32 v209, 0xffff0000, v8
	v_lshlrev_b32_e32 v210, 16, v9
	v_and_b32_e32 v211, 0xffff0000, v9
	v_pk_add_f32 v[242:243], v[142:143], v[208:209]
	v_pk_add_f32 v[244:245], v[144:145], v[210:211]
	v_pk_fma_f32 v[204:205], v[242:243], v[242:243], v[204:205]
	v_pk_fma_f32 v[206:207], v[244:245], v[244:245], v[206:207]
	s_nop 1
	v_add_f32_dpp v204, v204, v204 quad_perm:[1,0,3,2] row_mask:0xf bank_mask:0xf bound_ctrl:1
	v_add_f32_dpp v205, v205, v205 quad_perm:[1,0,3,2] row_mask:0xf bank_mask:0xf bound_ctrl:1
	v_add_f32_dpp v206, v206, v206 quad_perm:[1,0,3,2] row_mask:0xf bank_mask:0xf bound_ctrl:1
	v_add_f32_dpp v207, v207, v207 quad_perm:[1,0,3,2] row_mask:0xf bank_mask:0xf bound_ctrl:1
	v_add_f32_dpp v204, v204, v204 quad_perm:[2,3,0,1] row_mask:0xf bank_mask:0xf bound_ctrl:1
	v_add_f32_dpp v205, v205, v205 quad_perm:[2,3,0,1] row_mask:0xf bank_mask:0xf bound_ctrl:1
	v_add_f32_dpp v206, v206, v206 quad_perm:[2,3,0,1] row_mask:0xf bank_mask:0xf bound_ctrl:1
	v_add_f32_dpp v207, v207, v207 quad_perm:[2,3,0,1] row_mask:0xf bank_mask:0xf bound_ctrl:1
	v_add_f32_dpp v204, v204, v204 row_half_mirror row_mask:0xf bank_mask:0xf bound_ctrl:1
	v_add_f32_dpp v205, v205, v205 row_half_mirror row_mask:0xf bank_mask:0xf bound_ctrl:1
	v_add_f32_dpp v206, v206, v206 row_half_mirror row_mask:0xf bank_mask:0xf bound_ctrl:1
	v_add_f32_dpp v207, v207, v207 row_half_mirror row_mask:0xf bank_mask:0xf bound_ctrl:1
	v_add_f32_dpp v204, v204, v204 row_mirror row_mask:0xf bank_mask:0xf bound_ctrl:1
	v_add_f32_dpp v205, v205, v205 row_mirror row_mask:0xf bank_mask:0xf bound_ctrl:1
	v_add_f32_dpp v206, v206, v206 row_mirror row_mask:0xf bank_mask:0xf bound_ctrl:1
	v_add_f32_dpp v207, v207, v207 row_mirror row_mask:0xf bank_mask:0xf bound_ctrl:1
	v_fmamk_f32 v204, v204, 0x3c800000, v231
	v_fmamk_f32 v205, v205, 0x3c800000, v231
	v_fmamk_f32 v206, v206, 0x3c800000, v231
	v_fmamk_f32 v207, v207, 0x3c800000, v231
	v_rsq_f32_e32 v204, v204
	v_rsq_f32_e32 v205, v205
	v_rsq_f32_e32 v206, v206
	v_rsq_f32_e32 v207, v207
	v_lshlrev_b32_e32 v208, 16, v156
	v_lshlrev_b32_e32 v209, 16, v158
	v_lshlrev_b32_e32 v210, 16, v160
	v_lshlrev_b32_e32 v211, 16, v162
	v_pk_mul_f32 v[212:213], v[212:213], v[204:205]
	v_pk_mul_f32 v[214:215], v[214:215], v[206:207]
	v_pk_mul_f32 v[212:213], v[212:213], v[208:209]
	v_pk_mul_f32 v[214:215], v[214:215], v[210:211]
	v_and_b32_e32 v208, 0xffff0000, v156
	v_and_b32_e32 v209, 0xffff0000, v158
	v_and_b32_e32 v210, 0xffff0000, v160
	v_and_b32_e32 v211, 0xffff0000, v162
	v_pk_mul_f32 v[216:217], v[216:217], v[204:205]
	v_pk_mul_f32 v[218:219], v[218:219], v[206:207]
	v_pk_mul_f32 v[216:217], v[216:217], v[208:209]
	v_pk_mul_f32 v[218:219], v[218:219], v[210:211]
	v_lshlrev_b32_e32 v208, 16, v157
	v_lshlrev_b32_e32 v209, 16, v159
	v_lshlrev_b32_e32 v210, 16, v161
	v_lshlrev_b32_e32 v211, 16, v163
	v_pk_mul_f32 v[224:225], v[224:225], v[204:205]
	v_pk_mul_f32 v[226:227], v[226:227], v[206:207]
	v_pk_mul_f32 v[224:225], v[224:225], v[208:209]
	v_pk_mul_f32 v[226:227], v[226:227], v[210:211]
	v_and_b32_e32 v208, 0xffff0000, v157
	v_and_b32_e32 v209, 0xffff0000, v159
	v_and_b32_e32 v210, 0xffff0000, v161
	v_and_b32_e32 v211, 0xffff0000, v163
	v_pk_mul_f32 v[242:243], v[242:243], v[204:205]
	v_pk_mul_f32 v[244:245], v[244:245], v[206:207]
	v_pk_mul_f32 v[242:243], v[242:243], v[208:209]
	v_pk_mul_f32 v[244:245], v[244:245], v[210:211]
	v_cvt_pk_bf16_f32 v204, v212, v216
	v_cvt_pk_bf16_f32 v205, v224, v242
	v_cvt_pk_bf16_f32 v210, v213, v217
	v_cvt_pk_bf16_f32 v211, v225, v243
	v_cvt_pk_bf16_f32 v206, v214, v218
	v_cvt_pk_bf16_f32 v207, v226, v244
	v_cvt_pk_bf16_f32 v218, v215, v219
	v_cvt_pk_bf16_f32 v219, v227, v245
	v_and_b32_e32 v220, 1, v232
	v_mul_u32_u24_e32 v220, 0x7f8, v220
	v_add_u32_e32 v220, v21, v220
	s_mov_b32 vcc_lo, 0x55555555
	s_mov_b32 vcc_hi, 0x55555555
	v_cndmask_b32_dpp v208, v210, v204, vcc quad_perm:[1,0,3,2] row_mask:0xf bank_mask:0xf
	v_cndmask_b32_dpp v209, v211, v205, vcc quad_perm:[1,0,3,2] row_mask:0xf bank_mask:0xf
	v_cndmask_b32_dpp v216, v218, v206, vcc quad_perm:[1,0,3,2] row_mask:0xf bank_mask:0xf
	v_cndmask_b32_dpp v217, v219, v207, vcc quad_perm:[1,0,3,2] row_mask:0xf bank_mask:0xf
	s_not_b64 vcc, vcc
	v_cndmask_b32_dpp v210, v204, v210, vcc quad_perm:[1,0,3,2] row_mask:0xf bank_mask:0xf
	v_cndmask_b32_dpp v211, v205, v211, vcc quad_perm:[1,0,3,2] row_mask:0xf bank_mask:0xf
	v_cndmask_b32_dpp v218, v206, v218, vcc quad_perm:[1,0,3,2] row_mask:0xf bank_mask:0xf
	v_cndmask_b32_dpp v219, v207, v219, vcc quad_perm:[1,0,3,2] row_mask:0xf bank_mask:0xf
	global_store_dwordx4 v220, v[208:211], s[4:5]
	s_add_u32 s4, s10, 0x1000
	s_addc_u32 s5, s11, 0
	global_store_dwordx4 v220, v[216:219], s[4:5]
	s_add_u32 s4, s10, 0x1800
	s_addc_u32 s5, s11, 0
	s_cbranch_execz .LBB0_607
